# static priority: per-phase s_setprio flips removed from the 6 GEMM K loops, waves 4-7 raised to priority 1 once per tile, reset at loop exit
# speedup vs baseline: 1.0031x; 1.0031x over previous
; template <class Epi>
; DI void gemm_phase(PG8_LAS unsigned char* lds, const Gemm g, const StaticOrder& S, const Epi& E) {
;     ...
;     const int wid = __builtin_amdgcn_readfirstlane(tid >> 6), lane = tid & 63, wr = wid >> 2, wc = wid & 3, fr = lane & 15, fq = lane >> 4;
.LBB0_282:
	v_readfirstlane_b32 s100, v250
	s_nop 3
	s_lshr_b32 s100, s100, 8
	s_cmp_lg_u32 s100, 0
	s_cbranch_scc0 .Lprio_282
	s_setprio 1

; #define PG8_STAGE(bufoff, gbase, voff) do { _Pragma("unroll") for (int _i = 0; _i < 2; ++_i) \
;         __builtin_amdgcn_global_load_lds((const unsigned*)((const char*)(gbase) + (voff)[_i]), (PG8_LAS unsigned*)(lds + (bufoff) + ldsw + _i * 8192), 16, 0, 0); } while (0)
; #define PG8_LDA(dst, b, h) do { _Pragma("unroll") for (int m = 0; m < 4; ++m) _Pragma("unroll") for (int k = 0; k < 2; ++k) dst[m][k] = *(const PG8_LAS bf16x8*)(lds + PG8_SA(b, h) + aoff + m * 2048 + k * 1024); } while (0)
; #define PG8_LDB(dst, b, h) do { _Pragma("unroll") for (int n = 0; n < 2; ++n) _Pragma("unroll") for (int k = 0; k < 2; ++k) dst[n][k] = *(const PG8_LAS bf16x8*)(lds + PG8_SB(b, h) + boff + n * 2048 + k * 1024); } while (0)
; #define PG8_MMA(ai, bj, At, Bt) do { __builtin_amdgcn_s_setprio(1); _Pragma("unroll") for (int m = 0; m < 4; ++m) _Pragma("unroll") for (int n = 0; n < 2; ++n) _Pragma("unroll") for (int k = 0; k < 2; ++k) \
;         acc[ai][bj][m][n] = __builtin_amdgcn_mfma_f32_16x16x32_bf16(Bt[n][k], At[m][k], acc[ai][bj][m][n], 0, 0, 0); __builtin_amdgcn_s_setprio(0); } while (0)
; #define PG8_WAIT_V(n) asm volatile("s_waitcnt vmcnt(" #n ")" ::: "memory")
; #define PG8_WAIT_L(n) asm volatile("s_waitcnt lgkmcnt(" #n ")" ::: "memory")
; #define PG8_BAR __builtin_amdgcn_s_barrier()
; #define PG8_SCHED __builtin_amdgcn_sched_barrier(0)
; template <class Epi>
; DI void gemm_phase(PG8_LAS unsigned char* lds, const Gemm g, const StaticOrder& S, const Epi& E) {
;     ...
;             PG8_LDB(B0, 0, 0); PG8_LDB(B1, 0, 1); PG8_SCHED; PG8_LDA(At, 0, 0); PG8_STAGE(PG8_SA(1, 1), a1 + hstepA, voffA);
;             PG8_WAIT_V(8); PG8_WAIT_L(0); PG8_BAR; PG8_MMA(0, 0, At, B0); PG8_MMA(0, 1, At, B1); PG8_BAR; PG8_SCHED;
;             PG8_LDA(At, 0, 1); PG8_STAGE(PG8_SB(0, 0), b2, voffB); PG8_STAGE(PG8_SB(0, 1), b2 + hstepB, voffB); PG8_STAGE(PG8_SA(0, 0), a2, voffA);
;             PG8_WAIT_V(8); PG8_WAIT_L(0); PG8_BAR; PG8_MMA(1, 0, At, B0); PG8_MMA(1, 1, At, B1); PG8_BAR; PG8_SCHED;
.LBB0_283:
	ds_read_b128 v[92:95], v173
	ds_read_b128 v[96:99], v173 offset:1024
	ds_read_b128 v[112:115], v173 offset:2048
	ds_read_b128 v[116:119], v173 offset:3072
	ds_read_b128 v[162:165], v174
	ds_read_b128 v[166:169], v174 offset:1024
	ds_read_b128 v[176:179], v174 offset:2048
	ds_read_b128 v[180:183], v174 offset:3072
	s_add_u32 s18, s28, 0xfffc0080
	s_addc_u32 s19, s29, -1
	s_cmp_eq_u32 s53, 12
	s_cselect_b32 s35, s6, s19
	s_cselect_b32 s34, s17, s18
	s_cselect_b32 s31, s15, s52
	s_cselect_b32 s30, s50, s51
	v_lshl_add_u64 v[216:217], s[28:29], 0, v[154:155]
	s_add_i32 m0, s38, 0xc000
	ds_read_b128 v[184:187], v175
	ds_read_b128 v[188:191], v175 offset:1024
	ds_read_b128 v[192:195], v175 offset:2048
	ds_read_b128 v[196:199], v175 offset:3072
	ds_read_b128 v[200:203], v175 offset:4096
	ds_read_b128 v[204:207], v175 offset:5120
	ds_read_b128 v[208:211], v175 offset:6144
	ds_read_b128 v[212:215], v175 offset:7168
	global_load_lds_dwordx4 v[216:217], off
	v_lshl_add_u64 v[216:217], s[28:29], 0, v[156:157]
	s_add_i32 m0, s38, 0xe000
	s_nop 0
	global_load_lds_dwordx4 v[216:217], off
	s_waitcnt vmcnt(8)
	s_waitcnt lgkmcnt(0)
	s_barrier
	s_waitcnt lgkmcnt(0)
	v_mfma_f32_16x16x32_bf16 v[140:143], v[92:95], v[184:187], v[140:143]
	v_mfma_f32_16x16x32_bf16 v[136:139], v[112:115], v[184:187], v[136:139]
	v_mfma_f32_16x16x32_bf16 v[124:127], v[92:95], v[192:195], v[124:127]
	v_mfma_f32_16x16x32_bf16 v[120:123], v[112:115], v[192:195], v[120:123]
	v_mfma_f32_16x16x32_bf16 v[100:103], v[92:95], v[200:203], v[100:103]
	v_mfma_f32_16x16x32_bf16 v[88:91], v[112:115], v[200:203], v[88:91]
	v_mfma_f32_16x16x32_bf16 v[76:79], v[92:95], v[208:211], v[76:79]
	v_mfma_f32_16x16x32_bf16 v[72:75], v[112:115], v[208:211], v[72:75]
	v_mfma_f32_16x16x32_bf16 v[140:143], v[96:99], v[188:191], v[140:143]
	v_mfma_f32_16x16x32_bf16 v[136:139], v[116:119], v[188:191], v[136:139]
	v_mfma_f32_16x16x32_bf16 v[124:127], v[96:99], v[196:199], v[124:127]
	v_mfma_f32_16x16x32_bf16 v[120:123], v[116:119], v[196:199], v[120:123]
	v_mfma_f32_16x16x32_bf16 v[100:103], v[96:99], v[204:207], v[100:103]
	v_mfma_f32_16x16x32_bf16 v[88:91], v[116:119], v[204:207], v[88:91]
	v_mfma_f32_16x16x32_bf16 v[76:79], v[96:99], v[212:215], v[76:79]
	v_mfma_f32_16x16x32_bf16 v[72:75], v[116:119], v[212:215], v[72:75]
	v_mfma_f32_16x16x32_bf16 v[132:135], v[162:165], v[184:187], v[132:135]
	v_mfma_f32_16x16x32_bf16 v[128:131], v[176:179], v[184:187], v[128:131]
	v_mfma_f32_16x16x32_bf16 v[108:111], v[162:165], v[192:195], v[108:111]
	v_mfma_f32_16x16x32_bf16 v[104:107], v[176:179], v[192:195], v[104:107]
	v_mfma_f32_16x16x32_bf16 v[84:87], v[162:165], v[200:203], v[84:87]
	v_mfma_f32_16x16x32_bf16 v[80:83], v[176:179], v[200:203], v[80:83]
	v_mfma_f32_16x16x32_bf16 v[68:71], v[162:165], v[208:211], v[68:71]
	v_mfma_f32_16x16x32_bf16 v[64:67], v[176:179], v[208:211], v[64:67]
	v_mfma_f32_16x16x32_bf16 v[132:135], v[166:169], v[188:191], v[132:135]
	v_mfma_f32_16x16x32_bf16 v[128:131], v[180:183], v[188:191], v[128:131]
	v_mfma_f32_16x16x32_bf16 v[108:111], v[166:169], v[196:199], v[108:111]
	v_mfma_f32_16x16x32_bf16 v[104:107], v[180:183], v[196:199], v[104:107]
	v_mfma_f32_16x16x32_bf16 v[84:87], v[166:169], v[204:207], v[84:87]
	v_mfma_f32_16x16x32_bf16 v[80:83], v[180:183], v[204:207], v[80:83]
	v_mfma_f32_16x16x32_bf16 v[68:71], v[166:169], v[212:215], v[68:71]
	v_mfma_f32_16x16x32_bf16 v[64:67], v[180:183], v[212:215], v[64:67]
	s_barrier
	s_add_i32 s18, s47, s36
	v_lshl_add_u64 v[216:217], s[30:31], 0, v[148:149]
	s_mov_b32 m0, s18
	ds_read_b128 v[184:187], v175 offset:16384
	ds_read_b128 v[188:191], v175 offset:17408
	ds_read_b128 v[192:195], v175 offset:18432
	ds_read_b128 v[196:199], v175 offset:19456
	ds_read_b128 v[200:203], v175 offset:20480
	ds_read_b128 v[204:207], v175 offset:21504
	ds_read_b128 v[208:211], v175 offset:22528
	ds_read_b128 v[212:215], v175 offset:23552
	global_load_lds_dwordx4 v[216:217], off
	s_add_i32 m0, s18, 0x2000
	s_add_u32 s56, s30, 0x40000
	v_lshl_add_u64 v[218:219], s[30:31], 0, v[144:145]
	s_addc_u32 s57, s31, 0
	s_add_i32 s18, s48, s36
	global_load_lds_dwordx4 v[218:219], off
	v_lshl_add_u64 v[220:221], s[56:57], 0, v[148:149]
	s_mov_b32 m0, s18
	v_lshl_add_u64 v[222:223], s[34:35], 0, v[146:147]
	global_load_lds_dwordx4 v[220:221], off
	v_lshl_add_u64 v[220:221], s[56:57], 0, v[144:145]
	s_add_i32 m0, s18, 0x2000
	s_nop 0
	global_load_lds_dwordx4 v[220:221], off
	v_lshl_add_u64 v[220:221], s[34:35], 0, v[150:151]
	s_mov_b32 m0, s38
	s_nop 0
	global_load_lds_dwordx4 v[220:221], off
	s_mov_b32 m0, s39
	s_nop 0
	global_load_lds_dwordx4 v[222:223], off
	s_waitcnt vmcnt(8)
	s_waitcnt lgkmcnt(0)
	s_barrier
; #define PG8_STAGE(bufoff, gbase, voff) do { _Pragma("unroll") for (int _i = 0; _i < 2; ++_i) \
;         __builtin_amdgcn_global_load_lds((const unsigned*)((const char*)(gbase) + (voff)[_i]), (PG8_LAS unsigned*)(lds + (bufoff) + ldsw + _i * 8192), 16, 0, 0); } while (0)
; #define PG8_LDA(dst, b, h) do { _Pragma("unroll") for (int m = 0; m < 4; ++m) _Pragma("unroll") for (int k = 0; k < 2; ++k) dst[m][k] = *(const PG8_LAS bf16x8*)(lds + PG8_SA(b, h) + aoff + m * 2048 + k * 1024); } while (0)
; #define PG8_LDB(dst, b, h) do { _Pragma("unroll") for (int n = 0; n < 2; ++n) _Pragma("unroll") for (int k = 0; k < 2; ++k) dst[n][k] = *(const PG8_LAS bf16x8*)(lds + PG8_SB(b, h) + boff + n * 2048 + k * 1024); } while (0)
; #define PG8_MMA(ai, bj, At, Bt) do { __builtin_amdgcn_s_setprio(1); _Pragma("unroll") for (int m = 0; m < 4; ++m) _Pragma("unroll") for (int n = 0; n < 2; ++n) _Pragma("unroll") for (int k = 0; k < 2; ++k) \
;         acc[ai][bj][m][n] = __builtin_amdgcn_mfma_f32_16x16x32_bf16(Bt[n][k], At[m][k], acc[ai][bj][m][n], 0, 0, 0); __builtin_amdgcn_s_setprio(0); } while (0)
; #define PG8_WAIT_V(n) asm volatile("s_waitcnt vmcnt(" #n ")" ::: "memory")
; #define PG8_WAIT_L(n) asm volatile("s_waitcnt lgkmcnt(" #n ")" ::: "memory")
; #define PG8_BAR __builtin_amdgcn_s_barrier()
; #define PG8_SCHED __builtin_amdgcn_sched_barrier(0)
; template <class Epi>
; DI void gemm_phase(PG8_LAS unsigned char* lds, const Gemm g, const StaticOrder& S, const Epi& E) {
;     ...
;             PG8_WAIT_V(8); PG8_WAIT_L(0); PG8_BAR; PG8_MMA(1, 0, At, B0); PG8_MMA(1, 1, At, B1); PG8_BAR; PG8_SCHED;
;             PG8_LDB(B0, 1, 0); PG8_LDB(B1, 1, 1); PG8_SCHED; PG8_LDA(At, 1, 0); PG8_STAGE(PG8_SA(0, 1), a2 + hstepA, voffA);
;             PG8_WAIT_V(8); PG8_WAIT_L(0); PG8_BAR; PG8_MMA(0, 0, At, B0); PG8_MMA(0, 1, At, B1); PG8_BAR; PG8_SCHED;
	s_waitcnt lgkmcnt(0)
	v_mfma_f32_16x16x32_bf16 v[60:63], v[92:95], v[184:187], v[60:63]
	v_mfma_f32_16x16x32_bf16 v[56:59], v[112:115], v[184:187], v[56:59]
	v_mfma_f32_16x16x32_bf16 v[44:47], v[92:95], v[192:195], v[44:47]
	v_mfma_f32_16x16x32_bf16 v[40:43], v[112:115], v[192:195], v[40:43]
	v_mfma_f32_16x16x32_bf16 v[28:31], v[92:95], v[200:203], v[28:31]
	v_mfma_f32_16x16x32_bf16 v[24:27], v[112:115], v[200:203], v[24:27]
	v_mfma_f32_16x16x32_bf16 v[12:15], v[92:95], v[208:211], v[12:15]
	v_mfma_f32_16x16x32_bf16 v[8:11], v[112:115], v[208:211], v[8:11]
	v_mfma_f32_16x16x32_bf16 v[60:63], v[96:99], v[188:191], v[60:63]
	v_mfma_f32_16x16x32_bf16 v[56:59], v[116:119], v[188:191], v[56:59]
	v_mfma_f32_16x16x32_bf16 v[44:47], v[96:99], v[196:199], v[44:47]
	v_mfma_f32_16x16x32_bf16 v[40:43], v[116:119], v[196:199], v[40:43]
	v_mfma_f32_16x16x32_bf16 v[28:31], v[96:99], v[204:207], v[28:31]
	v_mfma_f32_16x16x32_bf16 v[24:27], v[116:119], v[204:207], v[24:27]
	v_mfma_f32_16x16x32_bf16 v[12:15], v[96:99], v[212:215], v[12:15]
	v_mfma_f32_16x16x32_bf16 v[8:11], v[116:119], v[212:215], v[8:11]
	v_mfma_f32_16x16x32_bf16 v[52:55], v[162:165], v[184:187], v[52:55]
	v_mfma_f32_16x16x32_bf16 v[48:51], v[176:179], v[184:187], v[48:51]
	v_mfma_f32_16x16x32_bf16 v[36:39], v[162:165], v[192:195], v[36:39]
	v_mfma_f32_16x16x32_bf16 v[32:35], v[176:179], v[192:195], v[32:35]
	v_mfma_f32_16x16x32_bf16 v[20:23], v[162:165], v[200:203], v[20:23]
	v_mfma_f32_16x16x32_bf16 v[16:19], v[176:179], v[200:203], v[16:19]
	v_mfma_f32_16x16x32_bf16 v[4:7], v[162:165], v[208:211], v[4:7]
	v_mfma_f32_16x16x32_bf16 v[0:3], v[176:179], v[208:211], v[0:3]
	v_mfma_f32_16x16x32_bf16 v[52:55], v[166:169], v[188:191], v[52:55]
	v_mfma_f32_16x16x32_bf16 v[48:51], v[180:183], v[188:191], v[48:51]
	v_mfma_f32_16x16x32_bf16 v[36:39], v[166:169], v[196:199], v[36:39]
	v_mfma_f32_16x16x32_bf16 v[32:35], v[180:183], v[196:199], v[32:35]
	v_mfma_f32_16x16x32_bf16 v[20:23], v[166:169], v[204:207], v[20:23]
	v_mfma_f32_16x16x32_bf16 v[16:19], v[180:183], v[204:207], v[16:19]
	v_mfma_f32_16x16x32_bf16 v[4:7], v[166:169], v[212:215], v[4:7]
	v_mfma_f32_16x16x32_bf16 v[0:3], v[180:183], v[212:215], v[0:3]
	s_barrier
	s_add_i32 s18, 16, 0x18000
	s_add_i32 s19, 16, 0x1c000
	v_add_u32_e32 v116, s18, v172
	v_add_u32_e32 v152, s19, v172
	ds_read_b128 v[92:95], v116
	ds_read_b128 v[96:99], v116 offset:1024
	ds_read_b128 v[112:115], v116 offset:2048
	ds_read_b128 v[116:119], v116 offset:3072
	ds_read_b128 v[162:165], v152
	ds_read_b128 v[166:169], v152 offset:1024
	ds_read_b128 v[176:179], v152 offset:2048
	ds_read_b128 v[180:183], v152 offset:3072
	s_add_u32 s34, s34, 0x40000
	s_addc_u32 s35, s35, 0
	s_mov_b32 m0, s40
	v_lshl_add_u64 v[226:227], s[34:35], 0, v[150:151]
	ds_read_b128 v[184:187], v175 offset:32768
	ds_read_b128 v[188:191], v175 offset:33792
	ds_read_b128 v[192:195], v175 offset:34816
	ds_read_b128 v[196:199], v175 offset:35840
	ds_read_b128 v[200:203], v175 offset:36864
	ds_read_b128 v[204:207], v175 offset:37888
	ds_read_b128 v[208:211], v175 offset:38912
	ds_read_b128 v[212:215], v175 offset:39936
	global_load_lds_dwordx4 v[226:227], off
	v_lshl_add_u64 v[226:227], s[34:35], 0, v[146:147]
	s_mov_b32 m0, s41
	s_nop 0
	global_load_lds_dwordx4 v[226:227], off
	s_waitcnt vmcnt(8)
	s_waitcnt lgkmcnt(0)
	s_barrier
	s_waitcnt lgkmcnt(0)
	v_mfma_f32_16x16x32_bf16 v[140:143], v[92:95], v[184:187], v[140:143]
	v_mfma_f32_16x16x32_bf16 v[136:139], v[112:115], v[184:187], v[136:139]
	v_mfma_f32_16x16x32_bf16 v[124:127], v[92:95], v[192:195], v[124:127]
	v_mfma_f32_16x16x32_bf16 v[120:123], v[112:115], v[192:195], v[120:123]
	v_mfma_f32_16x16x32_bf16 v[100:103], v[92:95], v[200:203], v[100:103]
	v_mfma_f32_16x16x32_bf16 v[88:91], v[112:115], v[200:203], v[88:91]
	v_mfma_f32_16x16x32_bf16 v[76:79], v[92:95], v[208:211], v[76:79]
	v_mfma_f32_16x16x32_bf16 v[72:75], v[112:115], v[208:211], v[72:75]
	v_mfma_f32_16x16x32_bf16 v[140:143], v[96:99], v[188:191], v[140:143]
	v_mfma_f32_16x16x32_bf16 v[136:139], v[116:119], v[188:191], v[136:139]
	v_mfma_f32_16x16x32_bf16 v[124:127], v[96:99], v[196:199], v[124:127]
	v_mfma_f32_16x16x32_bf16 v[120:123], v[116:119], v[196:199], v[120:123]
	v_mfma_f32_16x16x32_bf16 v[100:103], v[96:99], v[204:207], v[100:103]
	v_mfma_f32_16x16x32_bf16 v[88:91], v[116:119], v[204:207], v[88:91]
	v_mfma_f32_16x16x32_bf16 v[76:79], v[96:99], v[212:215], v[76:79]
	v_mfma_f32_16x16x32_bf16 v[72:75], v[116:119], v[212:215], v[72:75]
	v_mfma_f32_16x16x32_bf16 v[132:135], v[162:165], v[184:187], v[132:135]
	v_mfma_f32_16x16x32_bf16 v[128:131], v[176:179], v[184:187], v[128:131]
	v_mfma_f32_16x16x32_bf16 v[108:111], v[162:165], v[192:195], v[108:111]
	v_mfma_f32_16x16x32_bf16 v[104:107], v[176:179], v[192:195], v[104:107]
	v_mfma_f32_16x16x32_bf16 v[84:87], v[162:165], v[200:203], v[84:87]
	v_mfma_f32_16x16x32_bf16 v[80:83], v[176:179], v[200:203], v[80:83]
	v_mfma_f32_16x16x32_bf16 v[68:71], v[162:165], v[208:211], v[68:71]
	v_mfma_f32_16x16x32_bf16 v[64:67], v[176:179], v[208:211], v[64:67]
	v_mfma_f32_16x16x32_bf16 v[132:135], v[166:169], v[188:191], v[132:135]
	v_mfma_f32_16x16x32_bf16 v[128:131], v[180:183], v[188:191], v[128:131]
	v_mfma_f32_16x16x32_bf16 v[108:111], v[166:169], v[196:199], v[108:111]
	v_mfma_f32_16x16x32_bf16 v[104:107], v[180:183], v[196:199], v[104:107]
	v_mfma_f32_16x16x32_bf16 v[84:87], v[166:169], v[204:207], v[84:87]
	v_mfma_f32_16x16x32_bf16 v[80:83], v[180:183], v[204:207], v[80:83]
	v_mfma_f32_16x16x32_bf16 v[68:71], v[166:169], v[212:215], v[68:71]
	v_mfma_f32_16x16x32_bf16 v[64:67], v[180:183], v[212:215], v[64:67]
	s_barrier
; #define PG8_STAGE(bufoff, gbase, voff) do { _Pragma("unroll") for (int _i = 0; _i < 2; ++_i) \
;         __builtin_amdgcn_global_load_lds((const unsigned*)((const char*)(gbase) + (voff)[_i]), (PG8_LAS unsigned*)(lds + (bufoff) + ldsw + _i * 8192), 16, 0, 0); } while (0)
; #define PG8_LDA(dst, b, h) do { _Pragma("unroll") for (int m = 0; m < 4; ++m) _Pragma("unroll") for (int k = 0; k < 2; ++k) dst[m][k] = *(const PG8_LAS bf16x8*)(lds + PG8_SA(b, h) + aoff + m * 2048 + k * 1024); } while (0)
; #define PG8_MMA(ai, bj, At, Bt) do { __builtin_amdgcn_s_setprio(1); _Pragma("unroll") for (int m = 0; m < 4; ++m) _Pragma("unroll") for (int n = 0; n < 2; ++n) _Pragma("unroll") for (int k = 0; k < 2; ++k) \
;         acc[ai][bj][m][n] = __builtin_amdgcn_mfma_f32_16x16x32_bf16(Bt[n][k], At[m][k], acc[ai][bj][m][n], 0, 0, 0); __builtin_amdgcn_s_setprio(0); } while (0)
; #define PG8_WAIT_V(n) asm volatile("s_waitcnt vmcnt(" #n ")" ::: "memory")
; #define PG8_WAIT_L(n) asm volatile("s_waitcnt lgkmcnt(" #n ")" ::: "memory")
; #define PG8_BAR __builtin_amdgcn_s_barrier()
; #define PG8_SCHED __builtin_amdgcn_sched_barrier(0)
; template <class Epi>
; DI void gemm_phase(PG8_LAS unsigned char* lds, const Gemm g, const StaticOrder& S, const Epi& E) {
;     ...
;             PG8_LDA(At, 1, 1); PG8_STAGE(PG8_SB(1, 0), b3, voffB); PG8_STAGE(PG8_SB(1, 1), b3 + hstepB, voffB); PG8_STAGE(PG8_SA(1, 0), a3, voffA);
;             PG8_WAIT_V(8); PG8_WAIT_L(0); PG8_BAR; PG8_MMA(1, 0, At, B0); PG8_MMA(1, 1, At, B1); PG8_BAR; PG8_SCHED;
;         }
;         if (wr == 0) PG8_BAR;
	s_add_i32 s18, s18, s36
	v_lshl_add_u64 v[216:217], v[216:217], 0, s[10:11]
	s_mov_b32 m0, s18
	ds_read_b128 v[184:187], v175 offset:49152
	ds_read_b128 v[188:191], v175 offset:50176
	ds_read_b128 v[192:195], v175 offset:51200
	ds_read_b128 v[196:199], v175 offset:52224
	ds_read_b128 v[200:203], v175 offset:53248
	ds_read_b128 v[204:207], v175 offset:54272
	ds_read_b128 v[208:211], v175 offset:55296
	ds_read_b128 v[212:215], v175 offset:56320
	global_load_lds_dwordx4 v[216:217], off
	s_add_i32 m0, s18, 0x2000
	s_add_u32 s30, s30, 0x40080
	v_lshl_add_u64 v[216:217], v[218:219], 0, s[10:11]
	s_addc_u32 s31, s31, 0
	s_add_i32 s18, s19, s36
	global_load_lds_dwordx4 v[216:217], off
	v_lshl_add_u64 v[216:217], s[30:31], 0, v[148:149]
	s_mov_b32 m0, s18
	s_nop 0
	global_load_lds_dwordx4 v[216:217], off
	v_lshl_add_u64 v[216:217], s[30:31], 0, v[144:145]
	s_add_i32 m0, s18, 0x2000
	s_nop 0
	global_load_lds_dwordx4 v[216:217], off
	v_lshl_add_u64 v[216:217], v[220:221], 0, s[10:11]
	s_mov_b32 m0, s44
	s_nop 0
	global_load_lds_dwordx4 v[216:217], off
	v_lshl_add_u64 v[216:217], v[222:223], 0, s[10:11]
	s_mov_b32 m0, s45
	s_nop 0
	global_load_lds_dwordx4 v[216:217], off
	s_waitcnt vmcnt(8)
	s_waitcnt lgkmcnt(0)
	s_barrier
	s_waitcnt lgkmcnt(0)
	v_mfma_f32_16x16x32_bf16 v[60:63], v[92:95], v[184:187], v[60:63]
	v_mfma_f32_16x16x32_bf16 v[56:59], v[112:115], v[184:187], v[56:59]
	v_mfma_f32_16x16x32_bf16 v[44:47], v[92:95], v[192:195], v[44:47]
	v_mfma_f32_16x16x32_bf16 v[40:43], v[112:115], v[192:195], v[40:43]
	v_mfma_f32_16x16x32_bf16 v[28:31], v[92:95], v[200:203], v[28:31]
	v_mfma_f32_16x16x32_bf16 v[24:27], v[112:115], v[200:203], v[24:27]
	v_mfma_f32_16x16x32_bf16 v[12:15], v[92:95], v[208:211], v[12:15]
	v_mfma_f32_16x16x32_bf16 v[8:11], v[112:115], v[208:211], v[8:11]
	v_mfma_f32_16x16x32_bf16 v[60:63], v[96:99], v[188:191], v[60:63]
	v_mfma_f32_16x16x32_bf16 v[56:59], v[116:119], v[188:191], v[56:59]
	v_mfma_f32_16x16x32_bf16 v[44:47], v[96:99], v[196:199], v[44:47]
	v_mfma_f32_16x16x32_bf16 v[40:43], v[116:119], v[196:199], v[40:43]
	v_mfma_f32_16x16x32_bf16 v[28:31], v[96:99], v[204:207], v[28:31]
	v_mfma_f32_16x16x32_bf16 v[24:27], v[116:119], v[204:207], v[24:27]
	v_mfma_f32_16x16x32_bf16 v[12:15], v[96:99], v[212:215], v[12:15]
	v_mfma_f32_16x16x32_bf16 v[8:11], v[116:119], v[212:215], v[8:11]
	v_mfma_f32_16x16x32_bf16 v[52:55], v[162:165], v[184:187], v[52:55]
	v_mfma_f32_16x16x32_bf16 v[48:51], v[176:179], v[184:187], v[48:51]
	v_mfma_f32_16x16x32_bf16 v[36:39], v[162:165], v[192:195], v[36:39]
	v_mfma_f32_16x16x32_bf16 v[32:35], v[176:179], v[192:195], v[32:35]
	v_mfma_f32_16x16x32_bf16 v[20:23], v[162:165], v[200:203], v[20:23]
	v_mfma_f32_16x16x32_bf16 v[16:19], v[176:179], v[200:203], v[16:19]
	v_mfma_f32_16x16x32_bf16 v[4:7], v[162:165], v[208:211], v[4:7]
	v_mfma_f32_16x16x32_bf16 v[0:3], v[176:179], v[208:211], v[0:3]
	v_mfma_f32_16x16x32_bf16 v[52:55], v[166:169], v[188:191], v[52:55]
	v_mfma_f32_16x16x32_bf16 v[48:51], v[180:183], v[188:191], v[48:51]
	v_mfma_f32_16x16x32_bf16 v[36:39], v[166:169], v[196:199], v[36:39]
	v_mfma_f32_16x16x32_bf16 v[32:35], v[180:183], v[196:199], v[32:35]
	v_mfma_f32_16x16x32_bf16 v[20:23], v[166:169], v[204:207], v[20:23]
	v_mfma_f32_16x16x32_bf16 v[16:19], v[180:183], v[204:207], v[16:19]
	v_mfma_f32_16x16x32_bf16 v[4:7], v[166:169], v[212:215], v[4:7]
	v_mfma_f32_16x16x32_bf16 v[0:3], v[180:183], v[212:215], v[0:3]
	s_add_i32 s53, s53, 2
	s_add_u32 s28, s28, 0x100
	s_addc_u32 s29, s29, 0
	s_add_u32 s51, s51, 0x100
	s_addc_u32 s52, s52, 0
	s_cmp_gt_u32 s53, 13
	s_barrier
	s_cbranch_scc0 .LBB0_283
	s_setprio 0
	s_and_b64 vcc, exec, s[12:13]
	s_cbranch_vccz .LBB0_286
	s_barrier

; #define PG8_STAGE(bufoff, gbase, voff) do { _Pragma("unroll") for (int _i = 0; _i < 2; ++_i) \
;         __builtin_amdgcn_global_load_lds((const unsigned*)((const char*)(gbase) + (voff)[_i]), (PG8_LAS unsigned*)(lds + (bufoff) + ldsw + _i * 8192), 16, 0, 0); } while (0)
; #define PG8_LDA(dst, b, h) do { _Pragma("unroll") for (int m = 0; m < 4; ++m) _Pragma("unroll") for (int k = 0; k < 2; ++k) dst[m][k] = *(const PG8_LAS bf16x8*)(lds + PG8_SA(b, h) + aoff + m * 2048 + k * 1024); } while (0)
; #define PG8_LDB(dst, b, h) do { _Pragma("unroll") for (int n = 0; n < 2; ++n) _Pragma("unroll") for (int k = 0; k < 2; ++k) dst[n][k] = *(const PG8_LAS bf16x8*)(lds + PG8_SB(b, h) + boff + n * 2048 + k * 1024); } while (0)
; #define PG8_MMA(ai, bj, At, Bt) do { __builtin_amdgcn_s_setprio(1); _Pragma("unroll") for (int m = 0; m < 4; ++m) _Pragma("unroll") for (int n = 0; n < 2; ++n) _Pragma("unroll") for (int k = 0; k < 2; ++k) \
;         acc[ai][bj][m][n] = __builtin_amdgcn_mfma_f32_16x16x32_bf16(Bt[n][k], At[m][k], acc[ai][bj][m][n], 0, 0, 0); __builtin_amdgcn_s_setprio(0); } while (0)
; #define PG8_WAIT_V(n) asm volatile("s_waitcnt vmcnt(" #n ")" ::: "memory")
; #define PG8_WAIT_L(n) asm volatile("s_waitcnt lgkmcnt(" #n ")" ::: "memory")
; #define PG8_BAR __builtin_amdgcn_s_barrier()
; #define PG8_SCHED __builtin_amdgcn_sched_barrier(0)
; template <class Epi>
; DI void gemm_phase(PG8_LAS unsigned char* lds, const Gemm g, const StaticOrder& S, const Epi& E) {
;     ...
;             PG8_LDB(B0, 0, 0); PG8_LDB(B1, 0, 1); PG8_SCHED; PG8_LDA(At, 0, 0); PG8_STAGE(PG8_SA(1, 1), a1 + hstepA, voffA);
;             PG8_WAIT_V(8); PG8_WAIT_L(0); PG8_BAR; PG8_MMA(0, 0, At, B0); PG8_MMA(0, 1, At, B1); PG8_BAR; PG8_SCHED;
;             PG8_LDA(At, 0, 1); PG8_STAGE(PG8_SB(0, 0), b2, voffB); PG8_STAGE(PG8_SB(0, 1), b2 + hstepB, voffB); PG8_STAGE(PG8_SA(0, 0), a2, voffA);
;             PG8_WAIT_V(8); PG8_WAIT_L(0); PG8_BAR; PG8_MMA(1, 0, At, B0); PG8_MMA(1, 1, At, B1); PG8_BAR; PG8_SCHED;
.LBB0_655:
	ds_read_b128 v[152:155], v149
	ds_read_b128 v[156:159], v149 offset:1024
	ds_read_b128 v[160:163], v149 offset:2048
	ds_read_b128 v[164:167], v149 offset:3072
	ds_read_b128 v[168:171], v150
	ds_read_b128 v[172:175], v150 offset:1024
	ds_read_b128 v[176:179], v150 offset:2048
	ds_read_b128 v[184:187], v150 offset:3072
	s_add_u32 s26, s24, 0xfffe0080
	s_addc_u32 s27, s25, -1
	s_cmp_eq_u32 s51, 4
	s_cselect_b32 s29, s13, s27
	s_cselect_b32 s28, s47, s26
	s_cselect_b32 s27, s11, s50
	s_cselect_b32 s26, s48, s49
	v_lshl_add_u64 v[144:145], s[24:25], 0, v[136:137]
	s_add_i32 m0, s19, 0xc000
	ds_read_b128 v[188:191], v151
	ds_read_b128 v[192:195], v151 offset:1024
	ds_read_b128 v[196:199], v151 offset:2048
	ds_read_b128 v[200:203], v151 offset:3072
	ds_read_b128 v[204:207], v151 offset:4096
	ds_read_b128 v[208:211], v151 offset:5120
	ds_read_b128 v[212:215], v151 offset:6144
	ds_read_b128 v[216:219], v151 offset:7168
	global_load_lds_dwordx4 v[144:145], off
	v_lshl_add_u64 v[144:145], s[24:25], 0, v[138:139]
	s_add_i32 m0, s19, 0xe000
	s_nop 0
	global_load_lds_dwordx4 v[144:145], off
	s_waitcnt vmcnt(8)
	s_waitcnt lgkmcnt(0)
	s_barrier
	s_waitcnt lgkmcnt(0)
	v_mfma_f32_16x16x32_bf16 v[120:123], v[152:155], v[188:191], v[120:123]
	v_mfma_f32_16x16x32_bf16 v[124:127], v[160:163], v[188:191], v[124:127]
	v_mfma_f32_16x16x32_bf16 v[104:107], v[152:155], v[196:199], v[104:107]
	v_mfma_f32_16x16x32_bf16 v[108:111], v[160:163], v[196:199], v[108:111]
	v_mfma_f32_16x16x32_bf16 v[88:91], v[152:155], v[204:207], v[88:91]
	v_mfma_f32_16x16x32_bf16 v[92:95], v[160:163], v[204:207], v[92:95]
	v_mfma_f32_16x16x32_bf16 v[72:75], v[152:155], v[212:215], v[72:75]
	v_mfma_f32_16x16x32_bf16 v[76:79], v[160:163], v[212:215], v[76:79]
	v_mfma_f32_16x16x32_bf16 v[120:123], v[156:159], v[192:195], v[120:123]
	v_mfma_f32_16x16x32_bf16 v[124:127], v[164:167], v[192:195], v[124:127]
	v_mfma_f32_16x16x32_bf16 v[104:107], v[156:159], v[200:203], v[104:107]
	v_mfma_f32_16x16x32_bf16 v[108:111], v[164:167], v[200:203], v[108:111]
	v_mfma_f32_16x16x32_bf16 v[88:91], v[156:159], v[208:211], v[88:91]
	v_mfma_f32_16x16x32_bf16 v[92:95], v[164:167], v[208:211], v[92:95]
	v_mfma_f32_16x16x32_bf16 v[72:75], v[156:159], v[216:219], v[72:75]
	v_mfma_f32_16x16x32_bf16 v[76:79], v[164:167], v[216:219], v[76:79]
	v_mfma_f32_16x16x32_bf16 v[112:115], v[168:171], v[188:191], v[112:115]
	v_mfma_f32_16x16x32_bf16 v[116:119], v[176:179], v[188:191], v[116:119]
	v_mfma_f32_16x16x32_bf16 v[96:99], v[168:171], v[196:199], v[96:99]
	v_mfma_f32_16x16x32_bf16 v[100:103], v[176:179], v[196:199], v[100:103]
	v_mfma_f32_16x16x32_bf16 v[80:83], v[168:171], v[204:207], v[80:83]
	v_mfma_f32_16x16x32_bf16 v[84:87], v[176:179], v[204:207], v[84:87]
	v_mfma_f32_16x16x32_bf16 v[64:67], v[168:171], v[212:215], v[64:67]
	v_mfma_f32_16x16x32_bf16 v[68:71], v[176:179], v[212:215], v[68:71]
	v_mfma_f32_16x16x32_bf16 v[112:115], v[172:175], v[192:195], v[112:115]
	v_mfma_f32_16x16x32_bf16 v[116:119], v[184:187], v[192:195], v[116:119]
	v_mfma_f32_16x16x32_bf16 v[96:99], v[172:175], v[200:203], v[96:99]
	v_mfma_f32_16x16x32_bf16 v[100:103], v[184:187], v[200:203], v[100:103]
	v_mfma_f32_16x16x32_bf16 v[80:83], v[172:175], v[208:211], v[80:83]
	v_mfma_f32_16x16x32_bf16 v[84:87], v[184:187], v[208:211], v[84:87]
	v_mfma_f32_16x16x32_bf16 v[64:67], v[172:175], v[216:219], v[64:67]
	v_mfma_f32_16x16x32_bf16 v[68:71], v[184:187], v[216:219], v[68:71]
	s_barrier
	s_add_i32 s52, s44, s34
	v_lshl_add_u64 v[144:145], s[26:27], 0, v[130:131]
	s_mov_b32 m0, s52
	ds_read_b128 v[188:191], v151 offset:16384
	ds_read_b128 v[192:195], v151 offset:17408
	ds_read_b128 v[196:199], v151 offset:18432
	ds_read_b128 v[200:203], v151 offset:19456
	ds_read_b128 v[204:207], v151 offset:20480
	ds_read_b128 v[208:211], v151 offset:21504
	ds_read_b128 v[212:215], v151 offset:22528
	ds_read_b128 v[216:219], v151 offset:23552
	global_load_lds_dwordx4 v[144:145], off
	s_add_i32 m0, s52, 0x2000
	s_add_u32 s52, s26, 0x20000
	v_lshl_add_u64 v[180:181], s[26:27], 0, v[134:135]
	s_addc_u32 s53, s27, 0
	s_add_i32 s55, s45, s34
	global_load_lds_dwordx4 v[180:181], off
	v_lshl_add_u64 v[182:183], s[52:53], 0, v[130:131]
	s_mov_b32 m0, s55
	v_lshl_add_u64 v[220:221], s[28:29], 0, v[132:133]
	global_load_lds_dwordx4 v[182:183], off
	v_lshl_add_u64 v[182:183], s[52:53], 0, v[134:135]
	s_add_i32 m0, s55, 0x2000
	s_nop 0
	global_load_lds_dwordx4 v[182:183], off
	v_lshl_add_u64 v[182:183], s[28:29], 0, v[128:129]
	s_mov_b32 m0, s19
	s_nop 0
	global_load_lds_dwordx4 v[182:183], off
	s_mov_b32 m0, s35
	s_nop 0
	global_load_lds_dwordx4 v[220:221], off
	s_waitcnt vmcnt(8)
	s_waitcnt lgkmcnt(0)
	s_barrier
; #define PG8_STAGE(bufoff, gbase, voff) do { _Pragma("unroll") for (int _i = 0; _i < 2; ++_i) \
;         __builtin_amdgcn_global_load_lds((const unsigned*)((const char*)(gbase) + (voff)[_i]), (PG8_LAS unsigned*)(lds + (bufoff) + ldsw + _i * 8192), 16, 0, 0); } while (0)
; #define PG8_LDA(dst, b, h) do { _Pragma("unroll") for (int m = 0; m < 4; ++m) _Pragma("unroll") for (int k = 0; k < 2; ++k) dst[m][k] = *(const PG8_LAS bf16x8*)(lds + PG8_SA(b, h) + aoff + m * 2048 + k * 1024); } while (0)
; #define PG8_LDB(dst, b, h) do { _Pragma("unroll") for (int n = 0; n < 2; ++n) _Pragma("unroll") for (int k = 0; k < 2; ++k) dst[n][k] = *(const PG8_LAS bf16x8*)(lds + PG8_SB(b, h) + boff + n * 2048 + k * 1024); } while (0)
; #define PG8_MMA(ai, bj, At, Bt) do { __builtin_amdgcn_s_setprio(1); _Pragma("unroll") for (int m = 0; m < 4; ++m) _Pragma("unroll") for (int n = 0; n < 2; ++n) _Pragma("unroll") for (int k = 0; k < 2; ++k) \
;         acc[ai][bj][m][n] = __builtin_amdgcn_mfma_f32_16x16x32_bf16(Bt[n][k], At[m][k], acc[ai][bj][m][n], 0, 0, 0); __builtin_amdgcn_s_setprio(0); } while (0)
; #define PG8_WAIT_V(n) asm volatile("s_waitcnt vmcnt(" #n ")" ::: "memory")
; #define PG8_WAIT_L(n) asm volatile("s_waitcnt lgkmcnt(" #n ")" ::: "memory")
; #define PG8_BAR __builtin_amdgcn_s_barrier()
; #define PG8_SCHED __builtin_amdgcn_sched_barrier(0)
; template <class Epi>
; DI void gemm_phase(PG8_LAS unsigned char* lds, const Gemm g, const StaticOrder& S, const Epi& E) {
;     ...
;             PG8_WAIT_V(8); PG8_WAIT_L(0); PG8_BAR; PG8_MMA(1, 0, At, B0); PG8_MMA(1, 1, At, B1); PG8_BAR; PG8_SCHED;
;             PG8_LDB(B0, 1, 0); PG8_LDB(B1, 1, 1); PG8_SCHED; PG8_LDA(At, 1, 0); PG8_STAGE(PG8_SA(0, 1), a2 + hstepA, voffA);
;             PG8_WAIT_V(8); PG8_WAIT_L(0); PG8_BAR; PG8_MMA(0, 0, At, B0); PG8_MMA(0, 1, At, B1); PG8_BAR; PG8_SCHED;
	s_waitcnt lgkmcnt(0)
	v_mfma_f32_16x16x32_bf16 v[56:59], v[152:155], v[188:191], v[56:59]
	v_mfma_f32_16x16x32_bf16 v[60:63], v[160:163], v[188:191], v[60:63]
	v_mfma_f32_16x16x32_bf16 v[40:43], v[152:155], v[196:199], v[40:43]
	v_mfma_f32_16x16x32_bf16 v[44:47], v[160:163], v[196:199], v[44:47]
	v_mfma_f32_16x16x32_bf16 v[24:27], v[152:155], v[204:207], v[24:27]
	v_mfma_f32_16x16x32_bf16 v[28:31], v[160:163], v[204:207], v[28:31]
	v_mfma_f32_16x16x32_bf16 v[8:11], v[152:155], v[212:215], v[8:11]
	v_mfma_f32_16x16x32_bf16 v[12:15], v[160:163], v[212:215], v[12:15]
	v_mfma_f32_16x16x32_bf16 v[56:59], v[156:159], v[192:195], v[56:59]
	v_mfma_f32_16x16x32_bf16 v[60:63], v[164:167], v[192:195], v[60:63]
	v_mfma_f32_16x16x32_bf16 v[40:43], v[156:159], v[200:203], v[40:43]
	v_mfma_f32_16x16x32_bf16 v[44:47], v[164:167], v[200:203], v[44:47]
	v_mfma_f32_16x16x32_bf16 v[24:27], v[156:159], v[208:211], v[24:27]
	v_mfma_f32_16x16x32_bf16 v[28:31], v[164:167], v[208:211], v[28:31]
	v_mfma_f32_16x16x32_bf16 v[8:11], v[156:159], v[216:219], v[8:11]
	v_mfma_f32_16x16x32_bf16 v[12:15], v[164:167], v[216:219], v[12:15]
	v_mfma_f32_16x16x32_bf16 v[48:51], v[168:171], v[188:191], v[48:51]
	v_mfma_f32_16x16x32_bf16 v[52:55], v[176:179], v[188:191], v[52:55]
	v_mfma_f32_16x16x32_bf16 v[32:35], v[168:171], v[196:199], v[32:35]
	v_mfma_f32_16x16x32_bf16 v[36:39], v[176:179], v[196:199], v[36:39]
	v_mfma_f32_16x16x32_bf16 v[16:19], v[168:171], v[204:207], v[16:19]
	v_mfma_f32_16x16x32_bf16 v[20:23], v[176:179], v[204:207], v[20:23]
	v_mfma_f32_16x16x32_bf16 v[0:3], v[168:171], v[212:215], v[0:3]
	v_mfma_f32_16x16x32_bf16 v[4:7], v[176:179], v[212:215], v[4:7]
	v_mfma_f32_16x16x32_bf16 v[48:51], v[172:175], v[192:195], v[48:51]
	v_mfma_f32_16x16x32_bf16 v[52:55], v[184:187], v[192:195], v[52:55]
	v_mfma_f32_16x16x32_bf16 v[32:35], v[172:175], v[200:203], v[32:35]
	v_mfma_f32_16x16x32_bf16 v[36:39], v[184:187], v[200:203], v[36:39]
	v_mfma_f32_16x16x32_bf16 v[16:19], v[172:175], v[208:211], v[16:19]
	v_mfma_f32_16x16x32_bf16 v[20:23], v[184:187], v[208:211], v[20:23]
	v_mfma_f32_16x16x32_bf16 v[0:3], v[172:175], v[216:219], v[0:3]
	v_mfma_f32_16x16x32_bf16 v[4:7], v[184:187], v[216:219], v[4:7]
	s_barrier
	s_add_i32 s52, 16, 0x18000
	s_add_i32 s53, 16, 0x1c000
	v_add_u32_e32 v164, s52, v148
	v_add_u32_e32 v184, s53, v148
	ds_read_b128 v[152:155], v164
	ds_read_b128 v[156:159], v164 offset:1024
	ds_read_b128 v[160:163], v164 offset:2048
	ds_read_b128 v[164:167], v164 offset:3072
	ds_read_b128 v[168:171], v184
	ds_read_b128 v[172:175], v184 offset:1024
	ds_read_b128 v[176:179], v184 offset:2048
	ds_read_b128 v[184:187], v184 offset:3072
	s_add_u32 s28, s28, 0x20000
	s_addc_u32 s29, s29, 0
	s_mov_b32 m0, s36
	v_lshl_add_u64 v[222:223], s[28:29], 0, v[128:129]
	ds_read_b128 v[188:191], v151 offset:32768
	ds_read_b128 v[192:195], v151 offset:33792
	ds_read_b128 v[196:199], v151 offset:34816
	ds_read_b128 v[200:203], v151 offset:35840
	ds_read_b128 v[204:207], v151 offset:36864
	ds_read_b128 v[208:211], v151 offset:37888
	ds_read_b128 v[212:215], v151 offset:38912
	ds_read_b128 v[216:219], v151 offset:39936
	global_load_lds_dwordx4 v[222:223], off
	v_lshl_add_u64 v[222:223], s[28:29], 0, v[132:133]
	s_mov_b32 m0, s37
	s_nop 0
	global_load_lds_dwordx4 v[222:223], off
	s_waitcnt vmcnt(8)
	s_waitcnt lgkmcnt(0)
	s_barrier
	s_waitcnt lgkmcnt(0)
	v_mfma_f32_16x16x32_bf16 v[120:123], v[152:155], v[188:191], v[120:123]
	v_mfma_f32_16x16x32_bf16 v[124:127], v[160:163], v[188:191], v[124:127]
	v_mfma_f32_16x16x32_bf16 v[104:107], v[152:155], v[196:199], v[104:107]
	v_mfma_f32_16x16x32_bf16 v[108:111], v[160:163], v[196:199], v[108:111]
	v_mfma_f32_16x16x32_bf16 v[88:91], v[152:155], v[204:207], v[88:91]
	v_mfma_f32_16x16x32_bf16 v[92:95], v[160:163], v[204:207], v[92:95]
	v_mfma_f32_16x16x32_bf16 v[72:75], v[152:155], v[212:215], v[72:75]
	v_mfma_f32_16x16x32_bf16 v[76:79], v[160:163], v[212:215], v[76:79]
	v_mfma_f32_16x16x32_bf16 v[120:123], v[156:159], v[192:195], v[120:123]
	v_mfma_f32_16x16x32_bf16 v[124:127], v[164:167], v[192:195], v[124:127]
	v_mfma_f32_16x16x32_bf16 v[104:107], v[156:159], v[200:203], v[104:107]
	v_mfma_f32_16x16x32_bf16 v[108:111], v[164:167], v[200:203], v[108:111]
	v_mfma_f32_16x16x32_bf16 v[88:91], v[156:159], v[208:211], v[88:91]
	v_mfma_f32_16x16x32_bf16 v[92:95], v[164:167], v[208:211], v[92:95]
	v_mfma_f32_16x16x32_bf16 v[72:75], v[156:159], v[216:219], v[72:75]
	v_mfma_f32_16x16x32_bf16 v[76:79], v[164:167], v[216:219], v[76:79]
	v_mfma_f32_16x16x32_bf16 v[112:115], v[168:171], v[188:191], v[112:115]
	v_mfma_f32_16x16x32_bf16 v[116:119], v[176:179], v[188:191], v[116:119]
	v_mfma_f32_16x16x32_bf16 v[96:99], v[168:171], v[196:199], v[96:99]
	v_mfma_f32_16x16x32_bf16 v[100:103], v[176:179], v[196:199], v[100:103]
	v_mfma_f32_16x16x32_bf16 v[80:83], v[168:171], v[204:207], v[80:83]
	v_mfma_f32_16x16x32_bf16 v[84:87], v[176:179], v[204:207], v[84:87]
	v_mfma_f32_16x16x32_bf16 v[64:67], v[168:171], v[212:215], v[64:67]
	v_mfma_f32_16x16x32_bf16 v[68:71], v[176:179], v[212:215], v[68:71]
	v_mfma_f32_16x16x32_bf16 v[112:115], v[172:175], v[192:195], v[112:115]
	v_mfma_f32_16x16x32_bf16 v[116:119], v[184:187], v[192:195], v[116:119]
	v_mfma_f32_16x16x32_bf16 v[96:99], v[172:175], v[200:203], v[96:99]
	v_mfma_f32_16x16x32_bf16 v[100:103], v[184:187], v[200:203], v[100:103]
	v_mfma_f32_16x16x32_bf16 v[80:83], v[172:175], v[208:211], v[80:83]
	v_mfma_f32_16x16x32_bf16 v[84:87], v[184:187], v[208:211], v[84:87]
	v_mfma_f32_16x16x32_bf16 v[64:67], v[172:175], v[216:219], v[64:67]
	v_mfma_f32_16x16x32_bf16 v[68:71], v[184:187], v[216:219], v[68:71]
	s_barrier
; #define PG8_STAGE(bufoff, gbase, voff) do { _Pragma("unroll") for (int _i = 0; _i < 2; ++_i) \
;         __builtin_amdgcn_global_load_lds((const unsigned*)((const char*)(gbase) + (voff)[_i]), (PG8_LAS unsigned*)(lds + (bufoff) + ldsw + _i * 8192), 16, 0, 0); } while (0)
; #define PG8_LDA(dst, b, h) do { _Pragma("unroll") for (int m = 0; m < 4; ++m) _Pragma("unroll") for (int k = 0; k < 2; ++k) dst[m][k] = *(const PG8_LAS bf16x8*)(lds + PG8_SA(b, h) + aoff + m * 2048 + k * 1024); } while (0)
; #define PG8_MMA(ai, bj, At, Bt) do { __builtin_amdgcn_s_setprio(1); _Pragma("unroll") for (int m = 0; m < 4; ++m) _Pragma("unroll") for (int n = 0; n < 2; ++n) _Pragma("unroll") for (int k = 0; k < 2; ++k) \
;         acc[ai][bj][m][n] = __builtin_amdgcn_mfma_f32_16x16x32_bf16(Bt[n][k], At[m][k], acc[ai][bj][m][n], 0, 0, 0); __builtin_amdgcn_s_setprio(0); } while (0)
; #define PG8_WAIT_V(n) asm volatile("s_waitcnt vmcnt(" #n ")" ::: "memory")
; #define PG8_WAIT_L(n) asm volatile("s_waitcnt lgkmcnt(" #n ")" ::: "memory")
; #define PG8_BAR __builtin_amdgcn_s_barrier()
; #define PG8_SCHED __builtin_amdgcn_sched_barrier(0)
; template <class Epi>
; DI void gemm_phase(PG8_LAS unsigned char* lds, const Gemm g, const StaticOrder& S, const Epi& E) {
;     ...
;             PG8_LDA(At, 1, 1); PG8_STAGE(PG8_SB(1, 0), b3, voffB); PG8_STAGE(PG8_SB(1, 1), b3 + hstepB, voffB); PG8_STAGE(PG8_SA(1, 0), a3, voffA);
;             PG8_WAIT_V(8); PG8_WAIT_L(0); PG8_BAR; PG8_MMA(1, 0, At, B0); PG8_MMA(1, 1, At, B1); PG8_BAR; PG8_SCHED;
;         }
;         if (wr == 0) PG8_BAR;
	s_add_i32 s28, s52, s34
	v_lshl_add_u64 v[144:145], v[144:145], 0, s[6:7]
	s_mov_b32 m0, s28
	ds_read_b128 v[188:191], v151 offset:49152
	ds_read_b128 v[192:195], v151 offset:50176
	ds_read_b128 v[196:199], v151 offset:51200
	ds_read_b128 v[200:203], v151 offset:52224
	ds_read_b128 v[204:207], v151 offset:53248
	ds_read_b128 v[208:211], v151 offset:54272
	ds_read_b128 v[212:215], v151 offset:55296
	ds_read_b128 v[216:219], v151 offset:56320
	global_load_lds_dwordx4 v[144:145], off
	s_add_i32 m0, s28, 0x2000
	s_add_u32 s26, s26, 0x20080
	v_lshl_add_u64 v[144:145], v[180:181], 0, s[6:7]
	s_addc_u32 s27, s27, 0
	s_add_i32 s28, s53, s34
	global_load_lds_dwordx4 v[144:145], off
	v_lshl_add_u64 v[144:145], s[26:27], 0, v[130:131]
	s_mov_b32 m0, s28
	s_nop 0
	global_load_lds_dwordx4 v[144:145], off
	v_lshl_add_u64 v[144:145], s[26:27], 0, v[134:135]
	s_add_i32 m0, s28, 0x2000
	s_nop 0
	global_load_lds_dwordx4 v[144:145], off
	v_lshl_add_u64 v[144:145], v[182:183], 0, s[6:7]
	s_mov_b32 m0, s40
	s_nop 0
	global_load_lds_dwordx4 v[144:145], off
	v_lshl_add_u64 v[144:145], v[220:221], 0, s[6:7]
	s_mov_b32 m0, s41
	s_nop 0
	global_load_lds_dwordx4 v[144:145], off
	s_waitcnt vmcnt(8)
	s_waitcnt lgkmcnt(0)
	s_barrier
	s_waitcnt lgkmcnt(0)
	v_mfma_f32_16x16x32_bf16 v[56:59], v[152:155], v[188:191], v[56:59]
	v_mfma_f32_16x16x32_bf16 v[60:63], v[160:163], v[188:191], v[60:63]
	v_mfma_f32_16x16x32_bf16 v[40:43], v[152:155], v[196:199], v[40:43]
	v_mfma_f32_16x16x32_bf16 v[44:47], v[160:163], v[196:199], v[44:47]
	v_mfma_f32_16x16x32_bf16 v[24:27], v[152:155], v[204:207], v[24:27]
	v_mfma_f32_16x16x32_bf16 v[28:31], v[160:163], v[204:207], v[28:31]
	v_mfma_f32_16x16x32_bf16 v[8:11], v[152:155], v[212:215], v[8:11]
	v_mfma_f32_16x16x32_bf16 v[12:15], v[160:163], v[212:215], v[12:15]
	v_mfma_f32_16x16x32_bf16 v[56:59], v[156:159], v[192:195], v[56:59]
	v_mfma_f32_16x16x32_bf16 v[60:63], v[164:167], v[192:195], v[60:63]
	v_mfma_f32_16x16x32_bf16 v[40:43], v[156:159], v[200:203], v[40:43]
	v_mfma_f32_16x16x32_bf16 v[44:47], v[164:167], v[200:203], v[44:47]
	v_mfma_f32_16x16x32_bf16 v[24:27], v[156:159], v[208:211], v[24:27]
	v_mfma_f32_16x16x32_bf16 v[28:31], v[164:167], v[208:211], v[28:31]
	v_mfma_f32_16x16x32_bf16 v[8:11], v[156:159], v[216:219], v[8:11]
	v_mfma_f32_16x16x32_bf16 v[12:15], v[164:167], v[216:219], v[12:15]
	v_mfma_f32_16x16x32_bf16 v[48:51], v[168:171], v[188:191], v[48:51]
	v_mfma_f32_16x16x32_bf16 v[52:55], v[176:179], v[188:191], v[52:55]
	v_mfma_f32_16x16x32_bf16 v[32:35], v[168:171], v[196:199], v[32:35]
	v_mfma_f32_16x16x32_bf16 v[36:39], v[176:179], v[196:199], v[36:39]
	v_mfma_f32_16x16x32_bf16 v[16:19], v[168:171], v[204:207], v[16:19]
	v_mfma_f32_16x16x32_bf16 v[20:23], v[176:179], v[204:207], v[20:23]
	v_mfma_f32_16x16x32_bf16 v[0:3], v[168:171], v[212:215], v[0:3]
	v_mfma_f32_16x16x32_bf16 v[4:7], v[176:179], v[212:215], v[4:7]
	v_mfma_f32_16x16x32_bf16 v[48:51], v[172:175], v[192:195], v[48:51]
	v_mfma_f32_16x16x32_bf16 v[52:55], v[184:187], v[192:195], v[52:55]
	v_mfma_f32_16x16x32_bf16 v[32:35], v[172:175], v[200:203], v[32:35]
	v_mfma_f32_16x16x32_bf16 v[36:39], v[184:187], v[200:203], v[36:39]
	v_mfma_f32_16x16x32_bf16 v[16:19], v[172:175], v[208:211], v[16:19]
	v_mfma_f32_16x16x32_bf16 v[20:23], v[184:187], v[208:211], v[20:23]
	v_mfma_f32_16x16x32_bf16 v[0:3], v[172:175], v[216:219], v[0:3]
	v_mfma_f32_16x16x32_bf16 v[4:7], v[184:187], v[216:219], v[4:7]
	s_add_i32 s51, s51, 2
	s_add_u32 s24, s24, 0x100
	s_addc_u32 s25, s25, 0
	s_add_u32 s49, s49, 0x100
	s_addc_u32 s50, s50, 0
	s_cmp_gt_u32 s51, 5
	s_barrier
	s_cbranch_scc0 .LBB0_655
	s_setprio 0
	s_and_b64 vcc, exec, s[8:9]
	s_cbranch_vccz .LBB0_658
	s_barrier

; #define PG8_STAGE(bufoff, gbase, voff) do { _Pragma("unroll") for (int _i = 0; _i < 2; ++_i) \
;         __builtin_amdgcn_global_load_lds((const unsigned*)((const char*)(gbase) + (voff)[_i]), (PG8_LAS unsigned*)(lds + (bufoff) + ldsw + _i * 8192), 16, 0, 0); } while (0)
; #define PG8_LDA(dst, b, h) do { _Pragma("unroll") for (int m = 0; m < 4; ++m) _Pragma("unroll") for (int k = 0; k < 2; ++k) dst[m][k] = *(const PG8_LAS bf16x8*)(lds + PG8_SA(b, h) + aoff + m * 2048 + k * 1024); } while (0)
; #define PG8_LDB(dst, b, h) do { _Pragma("unroll") for (int n = 0; n < 2; ++n) _Pragma("unroll") for (int k = 0; k < 2; ++k) dst[n][k] = *(const PG8_LAS bf16x8*)(lds + PG8_SB(b, h) + boff + n * 2048 + k * 1024); } while (0)
; #define PG8_MMA(ai, bj, At, Bt) do { __builtin_amdgcn_s_setprio(1); _Pragma("unroll") for (int m = 0; m < 4; ++m) _Pragma("unroll") for (int n = 0; n < 2; ++n) _Pragma("unroll") for (int k = 0; k < 2; ++k) \
;         acc[ai][bj][m][n] = __builtin_amdgcn_mfma_f32_16x16x32_bf16(Bt[n][k], At[m][k], acc[ai][bj][m][n], 0, 0, 0); __builtin_amdgcn_s_setprio(0); } while (0)
; #define PG8_WAIT_V(n) asm volatile("s_waitcnt vmcnt(" #n ")" ::: "memory")
; #define PG8_WAIT_L(n) asm volatile("s_waitcnt lgkmcnt(" #n ")" ::: "memory")
; #define PG8_BAR __builtin_amdgcn_s_barrier()
; #define PG8_SCHED __builtin_amdgcn_sched_barrier(0)
; template <class Epi>
; DI void gemm_phase(PG8_LAS unsigned char* lds, const Gemm g, const StaticOrder& S, const Epi& E) {
;     ...
;             PG8_LDB(B0, 0, 0); PG8_LDB(B1, 0, 1); PG8_SCHED; PG8_LDA(At, 0, 0); PG8_STAGE(PG8_SA(1, 1), a1 + hstepA, voffA);
;             PG8_WAIT_V(8); PG8_WAIT_L(0); PG8_BAR; PG8_MMA(0, 0, At, B0); PG8_MMA(0, 1, At, B1); PG8_BAR; PG8_SCHED;
;             PG8_LDA(At, 0, 1); PG8_STAGE(PG8_SB(0, 0), b2, voffB); PG8_STAGE(PG8_SB(0, 1), b2 + hstepB, voffB); PG8_STAGE(PG8_SA(0, 0), a2, voffA);
;             PG8_WAIT_V(8); PG8_WAIT_L(0); PG8_BAR; PG8_MMA(1, 0, At, B0); PG8_MMA(1, 1, At, B1); PG8_BAR; PG8_SCHED;
.LBB0_852:
	ds_read_b128 v[144:147], v155
	ds_read_b128 v[148:151], v155 offset:1024
	ds_read_b128 v[158:161], v155 offset:2048
	ds_read_b128 v[162:165], v155 offset:3072
	ds_read_b128 v[166:169], v156
	ds_read_b128 v[170:173], v156 offset:1024
	ds_read_b128 v[174:177], v156 offset:2048
	ds_read_b128 v[178:181], v156 offset:3072
	s_add_u32 s30, s28, 0xfffc0080
	s_addc_u32 s31, s29, -1
	s_cmp_eq_u32 s91, 12
	s_cselect_b32 s35, s21, s31
	s_cselect_b32 s34, s85, s30
	s_cselect_b32 s31, s19, s90
	s_cselect_b32 s30, s86, s87
	v_lshl_add_u64 v[214:215], s[28:29], 0, v[136:137]
	s_add_i32 m0, s27, 0xc000
	ds_read_b128 v[182:185], v157
	ds_read_b128 v[186:189], v157 offset:1024
	ds_read_b128 v[190:193], v157 offset:2048
	ds_read_b128 v[194:197], v157 offset:3072
	ds_read_b128 v[198:201], v157 offset:4096
	ds_read_b128 v[202:205], v157 offset:5120
	ds_read_b128 v[206:209], v157 offset:6144
	ds_read_b128 v[210:213], v157 offset:7168
	global_load_lds_dwordx4 v[214:215], off
	v_lshl_add_u64 v[214:215], s[28:29], 0, v[138:139]
	s_add_i32 m0, s27, 0xe000
	s_nop 0
	global_load_lds_dwordx4 v[214:215], off
	s_waitcnt vmcnt(8)
	s_waitcnt lgkmcnt(0)
	s_barrier
	s_waitcnt lgkmcnt(0)
	v_mfma_f32_16x16x32_bf16 v[124:127], v[144:147], v[182:185], v[124:127]
	v_mfma_f32_16x16x32_bf16 v[120:123], v[158:161], v[182:185], v[120:123]
	v_mfma_f32_16x16x32_bf16 v[108:111], v[144:147], v[190:193], v[108:111]
	v_mfma_f32_16x16x32_bf16 v[104:107], v[158:161], v[190:193], v[104:107]
	v_mfma_f32_16x16x32_bf16 v[92:95], v[144:147], v[198:201], v[92:95]
	v_mfma_f32_16x16x32_bf16 v[88:91], v[158:161], v[198:201], v[88:91]
	v_mfma_f32_16x16x32_bf16 v[76:79], v[144:147], v[206:209], v[76:79]
	v_mfma_f32_16x16x32_bf16 v[72:75], v[158:161], v[206:209], v[72:75]
	v_mfma_f32_16x16x32_bf16 v[124:127], v[148:151], v[186:189], v[124:127]
	v_mfma_f32_16x16x32_bf16 v[120:123], v[162:165], v[186:189], v[120:123]
	v_mfma_f32_16x16x32_bf16 v[108:111], v[148:151], v[194:197], v[108:111]
	v_mfma_f32_16x16x32_bf16 v[104:107], v[162:165], v[194:197], v[104:107]
	v_mfma_f32_16x16x32_bf16 v[92:95], v[148:151], v[202:205], v[92:95]
	v_mfma_f32_16x16x32_bf16 v[88:91], v[162:165], v[202:205], v[88:91]
	v_mfma_f32_16x16x32_bf16 v[76:79], v[148:151], v[210:213], v[76:79]
	v_mfma_f32_16x16x32_bf16 v[72:75], v[162:165], v[210:213], v[72:75]
	v_mfma_f32_16x16x32_bf16 v[116:119], v[166:169], v[182:185], v[116:119]
	v_mfma_f32_16x16x32_bf16 v[112:115], v[174:177], v[182:185], v[112:115]
	v_mfma_f32_16x16x32_bf16 v[100:103], v[166:169], v[190:193], v[100:103]
	v_mfma_f32_16x16x32_bf16 v[96:99], v[174:177], v[190:193], v[96:99]
	v_mfma_f32_16x16x32_bf16 v[84:87], v[166:169], v[198:201], v[84:87]
	v_mfma_f32_16x16x32_bf16 v[80:83], v[174:177], v[198:201], v[80:83]
	v_mfma_f32_16x16x32_bf16 v[68:71], v[166:169], v[206:209], v[68:71]
	v_mfma_f32_16x16x32_bf16 v[64:67], v[174:177], v[206:209], v[64:67]
	v_mfma_f32_16x16x32_bf16 v[116:119], v[170:173], v[186:189], v[116:119]
	v_mfma_f32_16x16x32_bf16 v[112:115], v[178:181], v[186:189], v[112:115]
	v_mfma_f32_16x16x32_bf16 v[100:103], v[170:173], v[194:197], v[100:103]
	v_mfma_f32_16x16x32_bf16 v[96:99], v[178:181], v[194:197], v[96:99]
	v_mfma_f32_16x16x32_bf16 v[84:87], v[170:173], v[202:205], v[84:87]
	v_mfma_f32_16x16x32_bf16 v[80:83], v[178:181], v[202:205], v[80:83]
	v_mfma_f32_16x16x32_bf16 v[68:71], v[170:173], v[210:213], v[68:71]
	v_mfma_f32_16x16x32_bf16 v[64:67], v[178:181], v[210:213], v[64:67]
	s_barrier
	s_add_i32 s88, s50, s38
	v_lshl_add_u64 v[214:215], s[30:31], 0, v[130:131]
	s_mov_b32 m0, s88
	ds_read_b128 v[182:185], v157 offset:16384
	ds_read_b128 v[186:189], v157 offset:17408
	ds_read_b128 v[190:193], v157 offset:18432
	ds_read_b128 v[194:197], v157 offset:19456
	ds_read_b128 v[198:201], v157 offset:20480
	ds_read_b128 v[202:205], v157 offset:21504
	ds_read_b128 v[206:209], v157 offset:22528
	ds_read_b128 v[210:213], v157 offset:23552
	global_load_lds_dwordx4 v[214:215], off
	s_add_i32 m0, s88, 0x2000
	s_add_u32 s92, s30, 0x40000
	v_lshl_add_u64 v[216:217], s[30:31], 0, v[134:135]
	s_addc_u32 s93, s31, 0
	s_add_i32 s88, s51, s38
	global_load_lds_dwordx4 v[216:217], off
	v_lshl_add_u64 v[218:219], s[92:93], 0, v[130:131]
	s_mov_b32 m0, s88
	v_lshl_add_u64 v[220:221], s[34:35], 0, v[132:133]
	global_load_lds_dwordx4 v[218:219], off
	v_lshl_add_u64 v[218:219], s[92:93], 0, v[134:135]
	s_add_i32 m0, s88, 0x2000
	s_nop 0
	global_load_lds_dwordx4 v[218:219], off
	v_lshl_add_u64 v[218:219], s[34:35], 0, v[128:129]
	s_mov_b32 m0, s27
	s_nop 0
	global_load_lds_dwordx4 v[218:219], off
	s_mov_b32 m0, s39
	s_nop 0
	global_load_lds_dwordx4 v[220:221], off
	s_waitcnt vmcnt(8)
	s_waitcnt lgkmcnt(0)
	s_barrier
; #define PG8_STAGE(bufoff, gbase, voff) do { _Pragma("unroll") for (int _i = 0; _i < 2; ++_i) \
;         __builtin_amdgcn_global_load_lds((const unsigned*)((const char*)(gbase) + (voff)[_i]), (PG8_LAS unsigned*)(lds + (bufoff) + ldsw + _i * 8192), 16, 0, 0); } while (0)
; #define PG8_LDA(dst, b, h) do { _Pragma("unroll") for (int m = 0; m < 4; ++m) _Pragma("unroll") for (int k = 0; k < 2; ++k) dst[m][k] = *(const PG8_LAS bf16x8*)(lds + PG8_SA(b, h) + aoff + m * 2048 + k * 1024); } while (0)
; #define PG8_LDB(dst, b, h) do { _Pragma("unroll") for (int n = 0; n < 2; ++n) _Pragma("unroll") for (int k = 0; k < 2; ++k) dst[n][k] = *(const PG8_LAS bf16x8*)(lds + PG8_SB(b, h) + boff + n * 2048 + k * 1024); } while (0)
; #define PG8_MMA(ai, bj, At, Bt) do { __builtin_amdgcn_s_setprio(1); _Pragma("unroll") for (int m = 0; m < 4; ++m) _Pragma("unroll") for (int n = 0; n < 2; ++n) _Pragma("unroll") for (int k = 0; k < 2; ++k) \
;         acc[ai][bj][m][n] = __builtin_amdgcn_mfma_f32_16x16x32_bf16(Bt[n][k], At[m][k], acc[ai][bj][m][n], 0, 0, 0); __builtin_amdgcn_s_setprio(0); } while (0)
; #define PG8_WAIT_V(n) asm volatile("s_waitcnt vmcnt(" #n ")" ::: "memory")
; #define PG8_WAIT_L(n) asm volatile("s_waitcnt lgkmcnt(" #n ")" ::: "memory")
; #define PG8_BAR __builtin_amdgcn_s_barrier()
; #define PG8_SCHED __builtin_amdgcn_sched_barrier(0)
; template <class Epi>
; DI void gemm_phase(PG8_LAS unsigned char* lds, const Gemm g, const StaticOrder& S, const Epi& E) {
;     ...
;             PG8_WAIT_V(8); PG8_WAIT_L(0); PG8_BAR; PG8_MMA(1, 0, At, B0); PG8_MMA(1, 1, At, B1); PG8_BAR; PG8_SCHED;
;             PG8_LDB(B0, 1, 0); PG8_LDB(B1, 1, 1); PG8_SCHED; PG8_LDA(At, 1, 0); PG8_STAGE(PG8_SA(0, 1), a2 + hstepA, voffA);
;             PG8_WAIT_V(8); PG8_WAIT_L(0); PG8_BAR; PG8_MMA(0, 0, At, B0); PG8_MMA(0, 1, At, B1); PG8_BAR; PG8_SCHED;
	s_waitcnt lgkmcnt(0)
	v_mfma_f32_16x16x32_bf16 v[60:63], v[144:147], v[182:185], v[60:63]
	v_mfma_f32_16x16x32_bf16 v[56:59], v[158:161], v[182:185], v[56:59]
	v_mfma_f32_16x16x32_bf16 v[44:47], v[144:147], v[190:193], v[44:47]
	v_mfma_f32_16x16x32_bf16 v[40:43], v[158:161], v[190:193], v[40:43]
	v_mfma_f32_16x16x32_bf16 v[28:31], v[144:147], v[198:201], v[28:31]
	v_mfma_f32_16x16x32_bf16 v[24:27], v[158:161], v[198:201], v[24:27]
	v_mfma_f32_16x16x32_bf16 v[12:15], v[144:147], v[206:209], v[12:15]
	v_mfma_f32_16x16x32_bf16 v[8:11], v[158:161], v[206:209], v[8:11]
	v_mfma_f32_16x16x32_bf16 v[60:63], v[148:151], v[186:189], v[60:63]
	v_mfma_f32_16x16x32_bf16 v[56:59], v[162:165], v[186:189], v[56:59]
	v_mfma_f32_16x16x32_bf16 v[44:47], v[148:151], v[194:197], v[44:47]
	v_mfma_f32_16x16x32_bf16 v[40:43], v[162:165], v[194:197], v[40:43]
	v_mfma_f32_16x16x32_bf16 v[28:31], v[148:151], v[202:205], v[28:31]
	v_mfma_f32_16x16x32_bf16 v[24:27], v[162:165], v[202:205], v[24:27]
	v_mfma_f32_16x16x32_bf16 v[12:15], v[148:151], v[210:213], v[12:15]
	v_mfma_f32_16x16x32_bf16 v[8:11], v[162:165], v[210:213], v[8:11]
	v_mfma_f32_16x16x32_bf16 v[52:55], v[166:169], v[182:185], v[52:55]
	v_mfma_f32_16x16x32_bf16 v[48:51], v[174:177], v[182:185], v[48:51]
	v_mfma_f32_16x16x32_bf16 v[36:39], v[166:169], v[190:193], v[36:39]
	v_mfma_f32_16x16x32_bf16 v[32:35], v[174:177], v[190:193], v[32:35]
	v_mfma_f32_16x16x32_bf16 v[20:23], v[166:169], v[198:201], v[20:23]
	v_mfma_f32_16x16x32_bf16 v[16:19], v[174:177], v[198:201], v[16:19]
	v_mfma_f32_16x16x32_bf16 v[4:7], v[166:169], v[206:209], v[4:7]
	v_mfma_f32_16x16x32_bf16 v[0:3], v[174:177], v[206:209], v[0:3]
	v_mfma_f32_16x16x32_bf16 v[52:55], v[170:173], v[186:189], v[52:55]
	v_mfma_f32_16x16x32_bf16 v[48:51], v[178:181], v[186:189], v[48:51]
	v_mfma_f32_16x16x32_bf16 v[36:39], v[170:173], v[194:197], v[36:39]
	v_mfma_f32_16x16x32_bf16 v[32:35], v[178:181], v[194:197], v[32:35]
	v_mfma_f32_16x16x32_bf16 v[20:23], v[170:173], v[202:205], v[20:23]
	v_mfma_f32_16x16x32_bf16 v[16:19], v[178:181], v[202:205], v[16:19]
	v_mfma_f32_16x16x32_bf16 v[4:7], v[170:173], v[210:213], v[4:7]
	v_mfma_f32_16x16x32_bf16 v[0:3], v[178:181], v[210:213], v[0:3]
	s_barrier
	s_add_i32 s88, 16, 0x18000
	s_add_i32 s89, 16, 0x1c000
	v_add_u32_e32 v162, s88, v154
	v_add_u32_e32 v178, s89, v154
	ds_read_b128 v[144:147], v162
	ds_read_b128 v[148:151], v162 offset:1024
	ds_read_b128 v[158:161], v162 offset:2048
	ds_read_b128 v[162:165], v162 offset:3072
	ds_read_b128 v[166:169], v178
	ds_read_b128 v[170:173], v178 offset:1024
	ds_read_b128 v[174:177], v178 offset:2048
	ds_read_b128 v[178:181], v178 offset:3072
	s_add_u32 s34, s34, 0x40000
	s_addc_u32 s35, s35, 0
	s_mov_b32 m0, s40
	v_lshl_add_u64 v[222:223], s[34:35], 0, v[128:129]
	ds_read_b128 v[182:185], v157 offset:32768
	ds_read_b128 v[186:189], v157 offset:33792
	ds_read_b128 v[190:193], v157 offset:34816
	ds_read_b128 v[194:197], v157 offset:35840
	ds_read_b128 v[198:201], v157 offset:36864
	ds_read_b128 v[202:205], v157 offset:37888
	ds_read_b128 v[206:209], v157 offset:38912
	ds_read_b128 v[210:213], v157 offset:39936
	global_load_lds_dwordx4 v[222:223], off
	v_lshl_add_u64 v[222:223], s[34:35], 0, v[132:133]
	s_mov_b32 m0, s41
	s_nop 0
	global_load_lds_dwordx4 v[222:223], off
	s_waitcnt vmcnt(8)
	s_waitcnt lgkmcnt(0)
	s_barrier
	s_waitcnt lgkmcnt(0)
	v_mfma_f32_16x16x32_bf16 v[124:127], v[144:147], v[182:185], v[124:127]
	v_mfma_f32_16x16x32_bf16 v[120:123], v[158:161], v[182:185], v[120:123]
	v_mfma_f32_16x16x32_bf16 v[108:111], v[144:147], v[190:193], v[108:111]
	v_mfma_f32_16x16x32_bf16 v[104:107], v[158:161], v[190:193], v[104:107]
	v_mfma_f32_16x16x32_bf16 v[92:95], v[144:147], v[198:201], v[92:95]
	v_mfma_f32_16x16x32_bf16 v[88:91], v[158:161], v[198:201], v[88:91]
	v_mfma_f32_16x16x32_bf16 v[76:79], v[144:147], v[206:209], v[76:79]
	v_mfma_f32_16x16x32_bf16 v[72:75], v[158:161], v[206:209], v[72:75]
	v_mfma_f32_16x16x32_bf16 v[124:127], v[148:151], v[186:189], v[124:127]
	v_mfma_f32_16x16x32_bf16 v[120:123], v[162:165], v[186:189], v[120:123]
	v_mfma_f32_16x16x32_bf16 v[108:111], v[148:151], v[194:197], v[108:111]
	v_mfma_f32_16x16x32_bf16 v[104:107], v[162:165], v[194:197], v[104:107]
	v_mfma_f32_16x16x32_bf16 v[92:95], v[148:151], v[202:205], v[92:95]
	v_mfma_f32_16x16x32_bf16 v[88:91], v[162:165], v[202:205], v[88:91]
	v_mfma_f32_16x16x32_bf16 v[76:79], v[148:151], v[210:213], v[76:79]
	v_mfma_f32_16x16x32_bf16 v[72:75], v[162:165], v[210:213], v[72:75]
	v_mfma_f32_16x16x32_bf16 v[116:119], v[166:169], v[182:185], v[116:119]
	v_mfma_f32_16x16x32_bf16 v[112:115], v[174:177], v[182:185], v[112:115]
	v_mfma_f32_16x16x32_bf16 v[100:103], v[166:169], v[190:193], v[100:103]
	v_mfma_f32_16x16x32_bf16 v[96:99], v[174:177], v[190:193], v[96:99]
	v_mfma_f32_16x16x32_bf16 v[84:87], v[166:169], v[198:201], v[84:87]
	v_mfma_f32_16x16x32_bf16 v[80:83], v[174:177], v[198:201], v[80:83]
	v_mfma_f32_16x16x32_bf16 v[68:71], v[166:169], v[206:209], v[68:71]
	v_mfma_f32_16x16x32_bf16 v[64:67], v[174:177], v[206:209], v[64:67]
	v_mfma_f32_16x16x32_bf16 v[116:119], v[170:173], v[186:189], v[116:119]
	v_mfma_f32_16x16x32_bf16 v[112:115], v[178:181], v[186:189], v[112:115]
	v_mfma_f32_16x16x32_bf16 v[100:103], v[170:173], v[194:197], v[100:103]
	v_mfma_f32_16x16x32_bf16 v[96:99], v[178:181], v[194:197], v[96:99]
	v_mfma_f32_16x16x32_bf16 v[84:87], v[170:173], v[202:205], v[84:87]
	v_mfma_f32_16x16x32_bf16 v[80:83], v[178:181], v[202:205], v[80:83]
	v_mfma_f32_16x16x32_bf16 v[68:71], v[170:173], v[210:213], v[68:71]
	v_mfma_f32_16x16x32_bf16 v[64:67], v[178:181], v[210:213], v[64:67]
	s_barrier
; #define PG8_STAGE(bufoff, gbase, voff) do { _Pragma("unroll") for (int _i = 0; _i < 2; ++_i) \
;         __builtin_amdgcn_global_load_lds((const unsigned*)((const char*)(gbase) + (voff)[_i]), (PG8_LAS unsigned*)(lds + (bufoff) + ldsw + _i * 8192), 16, 0, 0); } while (0)
; #define PG8_LDA(dst, b, h) do { _Pragma("unroll") for (int m = 0; m < 4; ++m) _Pragma("unroll") for (int k = 0; k < 2; ++k) dst[m][k] = *(const PG8_LAS bf16x8*)(lds + PG8_SA(b, h) + aoff + m * 2048 + k * 1024); } while (0)
; #define PG8_MMA(ai, bj, At, Bt) do { __builtin_amdgcn_s_setprio(1); _Pragma("unroll") for (int m = 0; m < 4; ++m) _Pragma("unroll") for (int n = 0; n < 2; ++n) _Pragma("unroll") for (int k = 0; k < 2; ++k) \
;         acc[ai][bj][m][n] = __builtin_amdgcn_mfma_f32_16x16x32_bf16(Bt[n][k], At[m][k], acc[ai][bj][m][n], 0, 0, 0); __builtin_amdgcn_s_setprio(0); } while (0)
; #define PG8_WAIT_V(n) asm volatile("s_waitcnt vmcnt(" #n ")" ::: "memory")
; #define PG8_WAIT_L(n) asm volatile("s_waitcnt lgkmcnt(" #n ")" ::: "memory")
; #define PG8_BAR __builtin_amdgcn_s_barrier()
; #define PG8_SCHED __builtin_amdgcn_sched_barrier(0)
; template <class Epi>
; DI void gemm_phase(PG8_LAS unsigned char* lds, const Gemm g, const StaticOrder& S, const Epi& E) {
;     ...
;             PG8_LDA(At, 1, 1); PG8_STAGE(PG8_SB(1, 0), b3, voffB); PG8_STAGE(PG8_SB(1, 1), b3 + hstepB, voffB); PG8_STAGE(PG8_SA(1, 0), a3, voffA);
;             PG8_WAIT_V(8); PG8_WAIT_L(0); PG8_BAR; PG8_MMA(1, 0, At, B0); PG8_MMA(1, 1, At, B1); PG8_BAR; PG8_SCHED;
;         }
;         if (wr == 0) PG8_BAR;
	s_add_i32 s34, s88, s38
	v_lshl_add_u64 v[214:215], v[214:215], 0, s[14:15]
	s_mov_b32 m0, s34
	ds_read_b128 v[182:185], v157 offset:49152
	ds_read_b128 v[186:189], v157 offset:50176
	ds_read_b128 v[190:193], v157 offset:51200
	ds_read_b128 v[194:197], v157 offset:52224
	ds_read_b128 v[198:201], v157 offset:53248
	ds_read_b128 v[202:205], v157 offset:54272
	ds_read_b128 v[206:209], v157 offset:55296
	ds_read_b128 v[210:213], v157 offset:56320
	global_load_lds_dwordx4 v[214:215], off
	s_add_i32 m0, s34, 0x2000
	s_add_u32 s30, s30, 0x40080
	v_lshl_add_u64 v[214:215], v[216:217], 0, s[14:15]
	s_addc_u32 s31, s31, 0
	s_add_i32 s34, s89, s38
	global_load_lds_dwordx4 v[214:215], off
	v_lshl_add_u64 v[214:215], s[30:31], 0, v[130:131]
	s_mov_b32 m0, s34
	s_nop 0
	global_load_lds_dwordx4 v[214:215], off
	v_lshl_add_u64 v[214:215], s[30:31], 0, v[134:135]
	s_add_i32 m0, s34, 0x2000
	s_nop 0
	global_load_lds_dwordx4 v[214:215], off
	v_lshl_add_u64 v[214:215], v[218:219], 0, s[14:15]
	s_mov_b32 m0, s45
	s_nop 0
	global_load_lds_dwordx4 v[214:215], off
	v_lshl_add_u64 v[214:215], v[220:221], 0, s[14:15]
	s_mov_b32 m0, s46
	s_nop 0
	global_load_lds_dwordx4 v[214:215], off
	s_waitcnt vmcnt(8)
	s_waitcnt lgkmcnt(0)
	s_barrier
	s_waitcnt lgkmcnt(0)
	v_mfma_f32_16x16x32_bf16 v[60:63], v[144:147], v[182:185], v[60:63]
	v_mfma_f32_16x16x32_bf16 v[56:59], v[158:161], v[182:185], v[56:59]
	v_mfma_f32_16x16x32_bf16 v[44:47], v[144:147], v[190:193], v[44:47]
	v_mfma_f32_16x16x32_bf16 v[40:43], v[158:161], v[190:193], v[40:43]
	v_mfma_f32_16x16x32_bf16 v[28:31], v[144:147], v[198:201], v[28:31]
	v_mfma_f32_16x16x32_bf16 v[24:27], v[158:161], v[198:201], v[24:27]
	v_mfma_f32_16x16x32_bf16 v[12:15], v[144:147], v[206:209], v[12:15]
	v_mfma_f32_16x16x32_bf16 v[8:11], v[158:161], v[206:209], v[8:11]
	v_mfma_f32_16x16x32_bf16 v[60:63], v[148:151], v[186:189], v[60:63]
	v_mfma_f32_16x16x32_bf16 v[56:59], v[162:165], v[186:189], v[56:59]
	v_mfma_f32_16x16x32_bf16 v[44:47], v[148:151], v[194:197], v[44:47]
	v_mfma_f32_16x16x32_bf16 v[40:43], v[162:165], v[194:197], v[40:43]
	v_mfma_f32_16x16x32_bf16 v[28:31], v[148:151], v[202:205], v[28:31]
	v_mfma_f32_16x16x32_bf16 v[24:27], v[162:165], v[202:205], v[24:27]
	v_mfma_f32_16x16x32_bf16 v[12:15], v[148:151], v[210:213], v[12:15]
	v_mfma_f32_16x16x32_bf16 v[8:11], v[162:165], v[210:213], v[8:11]
	v_mfma_f32_16x16x32_bf16 v[52:55], v[166:169], v[182:185], v[52:55]
	v_mfma_f32_16x16x32_bf16 v[48:51], v[174:177], v[182:185], v[48:51]
	v_mfma_f32_16x16x32_bf16 v[36:39], v[166:169], v[190:193], v[36:39]
	v_mfma_f32_16x16x32_bf16 v[32:35], v[174:177], v[190:193], v[32:35]
	v_mfma_f32_16x16x32_bf16 v[20:23], v[166:169], v[198:201], v[20:23]
	v_mfma_f32_16x16x32_bf16 v[16:19], v[174:177], v[198:201], v[16:19]
	v_mfma_f32_16x16x32_bf16 v[4:7], v[166:169], v[206:209], v[4:7]
	v_mfma_f32_16x16x32_bf16 v[0:3], v[174:177], v[206:209], v[0:3]
	v_mfma_f32_16x16x32_bf16 v[52:55], v[170:173], v[186:189], v[52:55]
	v_mfma_f32_16x16x32_bf16 v[48:51], v[178:181], v[186:189], v[48:51]
	v_mfma_f32_16x16x32_bf16 v[36:39], v[170:173], v[194:197], v[36:39]
	v_mfma_f32_16x16x32_bf16 v[32:35], v[178:181], v[194:197], v[32:35]
	v_mfma_f32_16x16x32_bf16 v[20:23], v[170:173], v[202:205], v[20:23]
	v_mfma_f32_16x16x32_bf16 v[16:19], v[178:181], v[202:205], v[16:19]
	v_mfma_f32_16x16x32_bf16 v[4:7], v[170:173], v[210:213], v[4:7]
	v_mfma_f32_16x16x32_bf16 v[0:3], v[178:181], v[210:213], v[0:3]
	s_add_i32 s91, s91, 2
	s_add_u32 s28, s28, 0x100
	s_addc_u32 s29, s29, 0
	s_add_u32 s87, s87, 0x100
	s_addc_u32 s90, s90, 0
	s_cmp_gt_u32 s91, 13
	s_barrier
	s_cbranch_scc0 .LBB0_852
	s_setprio 0
	s_and_b64 vcc, exec, s[16:17]
	s_cbranch_vccz .LBB0_855
	s_barrier

; #define PG8_STAGE(bufoff, gbase, voff) do { _Pragma("unroll") for (int _i = 0; _i < 2; ++_i) \
;         __builtin_amdgcn_global_load_lds((const unsigned*)((const char*)(gbase) + (voff)[_i]), (PG8_LAS unsigned*)(lds + (bufoff) + ldsw + _i * 8192), 16, 0, 0); } while (0)
; #define PG8_LDA(dst, b, h) do { _Pragma("unroll") for (int m = 0; m < 4; ++m) _Pragma("unroll") for (int k = 0; k < 2; ++k) dst[m][k] = *(const PG8_LAS bf16x8*)(lds + PG8_SA(b, h) + aoff + m * 2048 + k * 1024); } while (0)
; #define PG8_LDB(dst, b, h) do { _Pragma("unroll") for (int n = 0; n < 2; ++n) _Pragma("unroll") for (int k = 0; k < 2; ++k) dst[n][k] = *(const PG8_LAS bf16x8*)(lds + PG8_SB(b, h) + boff + n * 2048 + k * 1024); } while (0)
; #define PG8_MMA(ai, bj, At, Bt) do { __builtin_amdgcn_s_setprio(1); _Pragma("unroll") for (int m = 0; m < 4; ++m) _Pragma("unroll") for (int n = 0; n < 2; ++n) _Pragma("unroll") for (int k = 0; k < 2; ++k) \
;         acc[ai][bj][m][n] = __builtin_amdgcn_mfma_f32_16x16x32_bf16(Bt[n][k], At[m][k], acc[ai][bj][m][n], 0, 0, 0); __builtin_amdgcn_s_setprio(0); } while (0)
; #define PG8_WAIT_V(n) asm volatile("s_waitcnt vmcnt(" #n ")" ::: "memory")
; #define PG8_WAIT_L(n) asm volatile("s_waitcnt lgkmcnt(" #n ")" ::: "memory")
; #define PG8_BAR __builtin_amdgcn_s_barrier()
; #define PG8_SCHED __builtin_amdgcn_sched_barrier(0)
; template <class Epi>
; DI void gemm_phase(PG8_LAS unsigned char* lds, const Gemm g, const StaticOrder& S, const Epi& E) {
;     ...
;             PG8_LDB(B0, 0, 0); PG8_LDB(B1, 0, 1); PG8_SCHED; PG8_LDA(At, 0, 0); PG8_STAGE(PG8_SA(1, 1), a1 + hstepA, voffA);
;             PG8_WAIT_V(8); PG8_WAIT_L(0); PG8_BAR; PG8_MMA(0, 0, At, B0); PG8_MMA(0, 1, At, B1); PG8_BAR; PG8_SCHED;
;             PG8_LDA(At, 0, 1); PG8_STAGE(PG8_SB(0, 0), b2, voffB); PG8_STAGE(PG8_SB(0, 1), b2 + hstepB, voffB); PG8_STAGE(PG8_SA(0, 0), a2, voffA);
;             PG8_WAIT_V(8); PG8_WAIT_L(0); PG8_BAR; PG8_MMA(1, 0, At, B0); PG8_MMA(1, 1, At, B1); PG8_BAR; PG8_SCHED;
.LBB0_928:
	ds_read_b128 v[144:147], v167
	ds_read_b128 v[148:151], v167 offset:1024
	ds_read_b128 v[152:155], v167 offset:2048
	ds_read_b128 v[156:159], v167 offset:3072
	ds_read_b128 v[160:163], v168
	ds_read_b128 v[170:173], v168 offset:1024
	ds_read_b128 v[174:177], v168 offset:2048
	ds_read_b128 v[178:181], v168 offset:3072
	s_add_u32 s40, s38, 0xfffc0080
	s_addc_u32 s41, s39, -1
	s_cmp_eq_u32 s91, 12
	s_cselect_b32 s43, s29, s41
	s_cselect_b32 s42, s85, s40
	s_cselect_b32 s41, s27, s90
	s_cselect_b32 s40, s86, s87
	v_lshl_add_u64 v[214:215], s[38:39], 0, v[136:137]
	s_add_i32 m0, s46, 0xc000
	ds_read_b128 v[182:185], v169
	ds_read_b128 v[186:189], v169 offset:1024
	ds_read_b128 v[190:193], v169 offset:2048
	ds_read_b128 v[194:197], v169 offset:3072
	ds_read_b128 v[198:201], v169 offset:4096
	ds_read_b128 v[202:205], v169 offset:5120
	ds_read_b128 v[206:209], v169 offset:6144
	ds_read_b128 v[210:213], v169 offset:7168
	global_load_lds_dwordx4 v[214:215], off
	v_lshl_add_u64 v[214:215], s[38:39], 0, v[138:139]
	s_add_i32 m0, s46, 0xe000
	s_nop 0
	global_load_lds_dwordx4 v[214:215], off
	s_waitcnt vmcnt(8)
	s_waitcnt lgkmcnt(0)
	s_barrier
	s_waitcnt lgkmcnt(0)
	v_mfma_f32_16x16x32_bf16 v[124:127], v[144:147], v[182:185], v[124:127]
	v_mfma_f32_16x16x32_bf16 v[120:123], v[152:155], v[182:185], v[120:123]
	v_mfma_f32_16x16x32_bf16 v[108:111], v[144:147], v[190:193], v[108:111]
	v_mfma_f32_16x16x32_bf16 v[104:107], v[152:155], v[190:193], v[104:107]
	v_mfma_f32_16x16x32_bf16 v[92:95], v[144:147], v[198:201], v[92:95]
	v_mfma_f32_16x16x32_bf16 v[88:91], v[152:155], v[198:201], v[88:91]
	v_mfma_f32_16x16x32_bf16 v[76:79], v[144:147], v[206:209], v[76:79]
	v_mfma_f32_16x16x32_bf16 v[72:75], v[152:155], v[206:209], v[72:75]
	v_mfma_f32_16x16x32_bf16 v[124:127], v[148:151], v[186:189], v[124:127]
	v_mfma_f32_16x16x32_bf16 v[120:123], v[156:159], v[186:189], v[120:123]
	v_mfma_f32_16x16x32_bf16 v[108:111], v[148:151], v[194:197], v[108:111]
	v_mfma_f32_16x16x32_bf16 v[104:107], v[156:159], v[194:197], v[104:107]
	v_mfma_f32_16x16x32_bf16 v[92:95], v[148:151], v[202:205], v[92:95]
	v_mfma_f32_16x16x32_bf16 v[88:91], v[156:159], v[202:205], v[88:91]
	v_mfma_f32_16x16x32_bf16 v[76:79], v[148:151], v[210:213], v[76:79]
	v_mfma_f32_16x16x32_bf16 v[72:75], v[156:159], v[210:213], v[72:75]
	v_mfma_f32_16x16x32_bf16 v[116:119], v[160:163], v[182:185], v[116:119]
	v_mfma_f32_16x16x32_bf16 v[112:115], v[174:177], v[182:185], v[112:115]
	v_mfma_f32_16x16x32_bf16 v[100:103], v[160:163], v[190:193], v[100:103]
	v_mfma_f32_16x16x32_bf16 v[96:99], v[174:177], v[190:193], v[96:99]
	v_mfma_f32_16x16x32_bf16 v[84:87], v[160:163], v[198:201], v[84:87]
	v_mfma_f32_16x16x32_bf16 v[80:83], v[174:177], v[198:201], v[80:83]
	v_mfma_f32_16x16x32_bf16 v[68:71], v[160:163], v[206:209], v[68:71]
	v_mfma_f32_16x16x32_bf16 v[64:67], v[174:177], v[206:209], v[64:67]
	v_mfma_f32_16x16x32_bf16 v[116:119], v[170:173], v[186:189], v[116:119]
	v_mfma_f32_16x16x32_bf16 v[112:115], v[178:181], v[186:189], v[112:115]
	v_mfma_f32_16x16x32_bf16 v[100:103], v[170:173], v[194:197], v[100:103]
	v_mfma_f32_16x16x32_bf16 v[96:99], v[178:181], v[194:197], v[96:99]
	v_mfma_f32_16x16x32_bf16 v[84:87], v[170:173], v[202:205], v[84:87]
	v_mfma_f32_16x16x32_bf16 v[80:83], v[178:181], v[202:205], v[80:83]
	v_mfma_f32_16x16x32_bf16 v[68:71], v[170:173], v[210:213], v[68:71]
	v_mfma_f32_16x16x32_bf16 v[64:67], v[178:181], v[210:213], v[64:67]
	s_barrier
	s_add_i32 s88, s57, s45
	v_lshl_add_u64 v[214:215], s[40:41], 0, v[130:131]
	s_mov_b32 m0, s88
	ds_read_b128 v[182:185], v169 offset:16384
	ds_read_b128 v[186:189], v169 offset:17408
	ds_read_b128 v[190:193], v169 offset:18432
	ds_read_b128 v[194:197], v169 offset:19456
	ds_read_b128 v[198:201], v169 offset:20480
	ds_read_b128 v[202:205], v169 offset:21504
	ds_read_b128 v[206:209], v169 offset:22528
	ds_read_b128 v[210:213], v169 offset:23552
	global_load_lds_dwordx4 v[214:215], off
	s_add_i32 m0, s88, 0x2000
	s_add_u32 s92, s40, 0x40000
	v_lshl_add_u64 v[216:217], s[40:41], 0, v[134:135]
	s_addc_u32 s93, s41, 0
	s_add_i32 s88, s76, s45
	global_load_lds_dwordx4 v[216:217], off
	v_lshl_add_u64 v[218:219], s[92:93], 0, v[130:131]
	s_mov_b32 m0, s88
	v_lshl_add_u64 v[220:221], s[42:43], 0, v[132:133]
	global_load_lds_dwordx4 v[218:219], off
	v_lshl_add_u64 v[218:219], s[92:93], 0, v[134:135]
	s_add_i32 m0, s88, 0x2000
	s_nop 0
	global_load_lds_dwordx4 v[218:219], off
	v_lshl_add_u64 v[218:219], s[42:43], 0, v[128:129]
	s_mov_b32 m0, s46
	s_nop 0
	global_load_lds_dwordx4 v[218:219], off
	s_mov_b32 m0, s47
	s_nop 0
	global_load_lds_dwordx4 v[220:221], off
	s_waitcnt vmcnt(8)
	s_waitcnt lgkmcnt(0)
	s_barrier
; #define PG8_STAGE(bufoff, gbase, voff) do { _Pragma("unroll") for (int _i = 0; _i < 2; ++_i) \
;         __builtin_amdgcn_global_load_lds((const unsigned*)((const char*)(gbase) + (voff)[_i]), (PG8_LAS unsigned*)(lds + (bufoff) + ldsw + _i * 8192), 16, 0, 0); } while (0)
; #define PG8_LDA(dst, b, h) do { _Pragma("unroll") for (int m = 0; m < 4; ++m) _Pragma("unroll") for (int k = 0; k < 2; ++k) dst[m][k] = *(const PG8_LAS bf16x8*)(lds + PG8_SA(b, h) + aoff + m * 2048 + k * 1024); } while (0)
; #define PG8_LDB(dst, b, h) do { _Pragma("unroll") for (int n = 0; n < 2; ++n) _Pragma("unroll") for (int k = 0; k < 2; ++k) dst[n][k] = *(const PG8_LAS bf16x8*)(lds + PG8_SB(b, h) + boff + n * 2048 + k * 1024); } while (0)
; #define PG8_MMA(ai, bj, At, Bt) do { __builtin_amdgcn_s_setprio(1); _Pragma("unroll") for (int m = 0; m < 4; ++m) _Pragma("unroll") for (int n = 0; n < 2; ++n) _Pragma("unroll") for (int k = 0; k < 2; ++k) \
;         acc[ai][bj][m][n] = __builtin_amdgcn_mfma_f32_16x16x32_bf16(Bt[n][k], At[m][k], acc[ai][bj][m][n], 0, 0, 0); __builtin_amdgcn_s_setprio(0); } while (0)
; #define PG8_WAIT_V(n) asm volatile("s_waitcnt vmcnt(" #n ")" ::: "memory")
; #define PG8_WAIT_L(n) asm volatile("s_waitcnt lgkmcnt(" #n ")" ::: "memory")
; #define PG8_BAR __builtin_amdgcn_s_barrier()
; #define PG8_SCHED __builtin_amdgcn_sched_barrier(0)
; template <class Epi>
; DI void gemm_phase(PG8_LAS unsigned char* lds, const Gemm g, const StaticOrder& S, const Epi& E) {
;     ...
;             PG8_WAIT_V(8); PG8_WAIT_L(0); PG8_BAR; PG8_MMA(1, 0, At, B0); PG8_MMA(1, 1, At, B1); PG8_BAR; PG8_SCHED;
;             PG8_LDB(B0, 1, 0); PG8_LDB(B1, 1, 1); PG8_SCHED; PG8_LDA(At, 1, 0); PG8_STAGE(PG8_SA(0, 1), a2 + hstepA, voffA);
;             PG8_WAIT_V(8); PG8_WAIT_L(0); PG8_BAR; PG8_MMA(0, 0, At, B0); PG8_MMA(0, 1, At, B1); PG8_BAR; PG8_SCHED;
	s_waitcnt lgkmcnt(0)
	v_mfma_f32_16x16x32_bf16 v[60:63], v[144:147], v[182:185], v[60:63]
	v_mfma_f32_16x16x32_bf16 v[56:59], v[152:155], v[182:185], v[56:59]
	v_mfma_f32_16x16x32_bf16 v[44:47], v[144:147], v[190:193], v[44:47]
	v_mfma_f32_16x16x32_bf16 v[40:43], v[152:155], v[190:193], v[40:43]
	v_mfma_f32_16x16x32_bf16 v[28:31], v[144:147], v[198:201], v[28:31]
	v_mfma_f32_16x16x32_bf16 v[24:27], v[152:155], v[198:201], v[24:27]
	v_mfma_f32_16x16x32_bf16 v[12:15], v[144:147], v[206:209], v[12:15]
	v_mfma_f32_16x16x32_bf16 v[8:11], v[152:155], v[206:209], v[8:11]
	v_mfma_f32_16x16x32_bf16 v[60:63], v[148:151], v[186:189], v[60:63]
	v_mfma_f32_16x16x32_bf16 v[56:59], v[156:159], v[186:189], v[56:59]
	v_mfma_f32_16x16x32_bf16 v[44:47], v[148:151], v[194:197], v[44:47]
	v_mfma_f32_16x16x32_bf16 v[40:43], v[156:159], v[194:197], v[40:43]
	v_mfma_f32_16x16x32_bf16 v[28:31], v[148:151], v[202:205], v[28:31]
	v_mfma_f32_16x16x32_bf16 v[24:27], v[156:159], v[202:205], v[24:27]
	v_mfma_f32_16x16x32_bf16 v[12:15], v[148:151], v[210:213], v[12:15]
	v_mfma_f32_16x16x32_bf16 v[8:11], v[156:159], v[210:213], v[8:11]
	v_mfma_f32_16x16x32_bf16 v[52:55], v[160:163], v[182:185], v[52:55]
	v_mfma_f32_16x16x32_bf16 v[48:51], v[174:177], v[182:185], v[48:51]
	v_mfma_f32_16x16x32_bf16 v[36:39], v[160:163], v[190:193], v[36:39]
	v_mfma_f32_16x16x32_bf16 v[32:35], v[174:177], v[190:193], v[32:35]
	v_mfma_f32_16x16x32_bf16 v[20:23], v[160:163], v[198:201], v[20:23]
	v_mfma_f32_16x16x32_bf16 v[16:19], v[174:177], v[198:201], v[16:19]
	v_mfma_f32_16x16x32_bf16 v[4:7], v[160:163], v[206:209], v[4:7]
	v_mfma_f32_16x16x32_bf16 v[0:3], v[174:177], v[206:209], v[0:3]
	v_mfma_f32_16x16x32_bf16 v[52:55], v[170:173], v[186:189], v[52:55]
	v_mfma_f32_16x16x32_bf16 v[48:51], v[178:181], v[186:189], v[48:51]
	v_mfma_f32_16x16x32_bf16 v[36:39], v[170:173], v[194:197], v[36:39]
	v_mfma_f32_16x16x32_bf16 v[32:35], v[178:181], v[194:197], v[32:35]
	v_mfma_f32_16x16x32_bf16 v[20:23], v[170:173], v[202:205], v[20:23]
	v_mfma_f32_16x16x32_bf16 v[16:19], v[178:181], v[202:205], v[16:19]
	v_mfma_f32_16x16x32_bf16 v[4:7], v[170:173], v[210:213], v[4:7]
	v_mfma_f32_16x16x32_bf16 v[0:3], v[178:181], v[210:213], v[0:3]
	s_barrier
	s_add_i32 s88, 16, 0x18000
	s_add_i32 s89, 16, 0x1c000
	v_add_u32_e32 v156, s88, v166
	v_add_u32_e32 v178, s89, v166
	ds_read_b128 v[144:147], v156
	ds_read_b128 v[148:151], v156 offset:1024
	ds_read_b128 v[152:155], v156 offset:2048
	ds_read_b128 v[156:159], v156 offset:3072
	ds_read_b128 v[160:163], v178
	ds_read_b128 v[170:173], v178 offset:1024
	ds_read_b128 v[174:177], v178 offset:2048
	ds_read_b128 v[178:181], v178 offset:3072
	s_add_u32 s42, s42, 0x40000
	s_addc_u32 s43, s43, 0
	s_mov_b32 m0, s48
	v_lshl_add_u64 v[222:223], s[42:43], 0, v[128:129]
	ds_read_b128 v[182:185], v169 offset:32768
	ds_read_b128 v[186:189], v169 offset:33792
	ds_read_b128 v[190:193], v169 offset:34816
	ds_read_b128 v[194:197], v169 offset:35840
	ds_read_b128 v[198:201], v169 offset:36864
	ds_read_b128 v[202:205], v169 offset:37888
	ds_read_b128 v[206:209], v169 offset:38912
	ds_read_b128 v[210:213], v169 offset:39936
	global_load_lds_dwordx4 v[222:223], off
	v_lshl_add_u64 v[222:223], s[42:43], 0, v[132:133]
	s_mov_b32 m0, s49
	s_nop 0
	global_load_lds_dwordx4 v[222:223], off
	s_waitcnt vmcnt(8)
	s_waitcnt lgkmcnt(0)
	s_barrier
	s_waitcnt lgkmcnt(0)
	v_mfma_f32_16x16x32_bf16 v[124:127], v[144:147], v[182:185], v[124:127]
	v_mfma_f32_16x16x32_bf16 v[120:123], v[152:155], v[182:185], v[120:123]
	v_mfma_f32_16x16x32_bf16 v[108:111], v[144:147], v[190:193], v[108:111]
	v_mfma_f32_16x16x32_bf16 v[104:107], v[152:155], v[190:193], v[104:107]
	v_mfma_f32_16x16x32_bf16 v[92:95], v[144:147], v[198:201], v[92:95]
	v_mfma_f32_16x16x32_bf16 v[88:91], v[152:155], v[198:201], v[88:91]
	v_mfma_f32_16x16x32_bf16 v[76:79], v[144:147], v[206:209], v[76:79]
	v_mfma_f32_16x16x32_bf16 v[72:75], v[152:155], v[206:209], v[72:75]
	v_mfma_f32_16x16x32_bf16 v[124:127], v[148:151], v[186:189], v[124:127]
	v_mfma_f32_16x16x32_bf16 v[120:123], v[156:159], v[186:189], v[120:123]
	v_mfma_f32_16x16x32_bf16 v[108:111], v[148:151], v[194:197], v[108:111]
	v_mfma_f32_16x16x32_bf16 v[104:107], v[156:159], v[194:197], v[104:107]
	v_mfma_f32_16x16x32_bf16 v[92:95], v[148:151], v[202:205], v[92:95]
	v_mfma_f32_16x16x32_bf16 v[88:91], v[156:159], v[202:205], v[88:91]
	v_mfma_f32_16x16x32_bf16 v[76:79], v[148:151], v[210:213], v[76:79]
	v_mfma_f32_16x16x32_bf16 v[72:75], v[156:159], v[210:213], v[72:75]
	v_mfma_f32_16x16x32_bf16 v[116:119], v[160:163], v[182:185], v[116:119]
	v_mfma_f32_16x16x32_bf16 v[112:115], v[174:177], v[182:185], v[112:115]
	v_mfma_f32_16x16x32_bf16 v[100:103], v[160:163], v[190:193], v[100:103]
	v_mfma_f32_16x16x32_bf16 v[96:99], v[174:177], v[190:193], v[96:99]
	v_mfma_f32_16x16x32_bf16 v[84:87], v[160:163], v[198:201], v[84:87]
	v_mfma_f32_16x16x32_bf16 v[80:83], v[174:177], v[198:201], v[80:83]
	v_mfma_f32_16x16x32_bf16 v[68:71], v[160:163], v[206:209], v[68:71]
	v_mfma_f32_16x16x32_bf16 v[64:67], v[174:177], v[206:209], v[64:67]
	v_mfma_f32_16x16x32_bf16 v[116:119], v[170:173], v[186:189], v[116:119]
	v_mfma_f32_16x16x32_bf16 v[112:115], v[178:181], v[186:189], v[112:115]
	v_mfma_f32_16x16x32_bf16 v[100:103], v[170:173], v[194:197], v[100:103]
	v_mfma_f32_16x16x32_bf16 v[96:99], v[178:181], v[194:197], v[96:99]
	v_mfma_f32_16x16x32_bf16 v[84:87], v[170:173], v[202:205], v[84:87]
	v_mfma_f32_16x16x32_bf16 v[80:83], v[178:181], v[202:205], v[80:83]
	v_mfma_f32_16x16x32_bf16 v[68:71], v[170:173], v[210:213], v[68:71]
	v_mfma_f32_16x16x32_bf16 v[64:67], v[178:181], v[210:213], v[64:67]
	s_barrier
; #define PG8_STAGE(bufoff, gbase, voff) do { _Pragma("unroll") for (int _i = 0; _i < 2; ++_i) \
;         __builtin_amdgcn_global_load_lds((const unsigned*)((const char*)(gbase) + (voff)[_i]), (PG8_LAS unsigned*)(lds + (bufoff) + ldsw + _i * 8192), 16, 0, 0); } while (0)
; #define PG8_LDA(dst, b, h) do { _Pragma("unroll") for (int m = 0; m < 4; ++m) _Pragma("unroll") for (int k = 0; k < 2; ++k) dst[m][k] = *(const PG8_LAS bf16x8*)(lds + PG8_SA(b, h) + aoff + m * 2048 + k * 1024); } while (0)
; #define PG8_MMA(ai, bj, At, Bt) do { __builtin_amdgcn_s_setprio(1); _Pragma("unroll") for (int m = 0; m < 4; ++m) _Pragma("unroll") for (int n = 0; n < 2; ++n) _Pragma("unroll") for (int k = 0; k < 2; ++k) \
;         acc[ai][bj][m][n] = __builtin_amdgcn_mfma_f32_16x16x32_bf16(Bt[n][k], At[m][k], acc[ai][bj][m][n], 0, 0, 0); __builtin_amdgcn_s_setprio(0); } while (0)
; #define PG8_WAIT_V(n) asm volatile("s_waitcnt vmcnt(" #n ")" ::: "memory")
; #define PG8_WAIT_L(n) asm volatile("s_waitcnt lgkmcnt(" #n ")" ::: "memory")
; #define PG8_BAR __builtin_amdgcn_s_barrier()
; #define PG8_SCHED __builtin_amdgcn_sched_barrier(0)
; template <class Epi>
; DI void gemm_phase(PG8_LAS unsigned char* lds, const Gemm g, const StaticOrder& S, const Epi& E) {
;     ...
;             PG8_LDA(At, 1, 1); PG8_STAGE(PG8_SB(1, 0), b3, voffB); PG8_STAGE(PG8_SB(1, 1), b3 + hstepB, voffB); PG8_STAGE(PG8_SA(1, 0), a3, voffA);
;             PG8_WAIT_V(8); PG8_WAIT_L(0); PG8_BAR; PG8_MMA(1, 0, At, B0); PG8_MMA(1, 1, At, B1); PG8_BAR; PG8_SCHED;
;         }
;         if (wr == 0) PG8_BAR;
	s_add_i32 s42, s88, s45
	v_lshl_add_u64 v[214:215], v[214:215], 0, s[10:11]
	s_mov_b32 m0, s42
	ds_read_b128 v[182:185], v169 offset:49152
	ds_read_b128 v[186:189], v169 offset:50176
	ds_read_b128 v[190:193], v169 offset:51200
	ds_read_b128 v[194:197], v169 offset:52224
	ds_read_b128 v[198:201], v169 offset:53248
	ds_read_b128 v[202:205], v169 offset:54272
	ds_read_b128 v[206:209], v169 offset:55296
	ds_read_b128 v[210:213], v169 offset:56320
	global_load_lds_dwordx4 v[214:215], off
	s_add_i32 m0, s42, 0x2000
	s_add_u32 s40, s40, 0x40080
	v_lshl_add_u64 v[214:215], v[216:217], 0, s[10:11]
	s_addc_u32 s41, s41, 0
	s_add_i32 s42, s89, s45
	global_load_lds_dwordx4 v[214:215], off
	v_lshl_add_u64 v[214:215], s[40:41], 0, v[130:131]
	s_mov_b32 m0, s42
	s_nop 0
	global_load_lds_dwordx4 v[214:215], off
	v_lshl_add_u64 v[214:215], s[40:41], 0, v[134:135]
	s_add_i32 m0, s42, 0x2000
	s_nop 0
	global_load_lds_dwordx4 v[214:215], off
	v_lshl_add_u64 v[214:215], v[218:219], 0, s[10:11]
	s_mov_b32 m0, s53
	s_nop 0
	global_load_lds_dwordx4 v[214:215], off
	v_lshl_add_u64 v[214:215], v[220:221], 0, s[10:11]
	s_mov_b32 m0, s54
	s_nop 0
	global_load_lds_dwordx4 v[214:215], off
	s_waitcnt vmcnt(8)
	s_waitcnt lgkmcnt(0)
	s_barrier
	s_waitcnt lgkmcnt(0)
	v_mfma_f32_16x16x32_bf16 v[60:63], v[144:147], v[182:185], v[60:63]
	v_mfma_f32_16x16x32_bf16 v[56:59], v[152:155], v[182:185], v[56:59]
	v_mfma_f32_16x16x32_bf16 v[44:47], v[144:147], v[190:193], v[44:47]
	v_mfma_f32_16x16x32_bf16 v[40:43], v[152:155], v[190:193], v[40:43]
	v_mfma_f32_16x16x32_bf16 v[28:31], v[144:147], v[198:201], v[28:31]
	v_mfma_f32_16x16x32_bf16 v[24:27], v[152:155], v[198:201], v[24:27]
	v_mfma_f32_16x16x32_bf16 v[12:15], v[144:147], v[206:209], v[12:15]
	v_mfma_f32_16x16x32_bf16 v[8:11], v[152:155], v[206:209], v[8:11]
	v_mfma_f32_16x16x32_bf16 v[60:63], v[148:151], v[186:189], v[60:63]
	v_mfma_f32_16x16x32_bf16 v[56:59], v[156:159], v[186:189], v[56:59]
	v_mfma_f32_16x16x32_bf16 v[44:47], v[148:151], v[194:197], v[44:47]
	v_mfma_f32_16x16x32_bf16 v[40:43], v[156:159], v[194:197], v[40:43]
	v_mfma_f32_16x16x32_bf16 v[28:31], v[148:151], v[202:205], v[28:31]
	v_mfma_f32_16x16x32_bf16 v[24:27], v[156:159], v[202:205], v[24:27]
	v_mfma_f32_16x16x32_bf16 v[12:15], v[148:151], v[210:213], v[12:15]
	v_mfma_f32_16x16x32_bf16 v[8:11], v[156:159], v[210:213], v[8:11]
	v_mfma_f32_16x16x32_bf16 v[52:55], v[160:163], v[182:185], v[52:55]
	v_mfma_f32_16x16x32_bf16 v[48:51], v[174:177], v[182:185], v[48:51]
	v_mfma_f32_16x16x32_bf16 v[36:39], v[160:163], v[190:193], v[36:39]
	v_mfma_f32_16x16x32_bf16 v[32:35], v[174:177], v[190:193], v[32:35]
	v_mfma_f32_16x16x32_bf16 v[20:23], v[160:163], v[198:201], v[20:23]
	v_mfma_f32_16x16x32_bf16 v[16:19], v[174:177], v[198:201], v[16:19]
	v_mfma_f32_16x16x32_bf16 v[4:7], v[160:163], v[206:209], v[4:7]
	v_mfma_f32_16x16x32_bf16 v[0:3], v[174:177], v[206:209], v[0:3]
	v_mfma_f32_16x16x32_bf16 v[52:55], v[170:173], v[186:189], v[52:55]
	v_mfma_f32_16x16x32_bf16 v[48:51], v[178:181], v[186:189], v[48:51]
	v_mfma_f32_16x16x32_bf16 v[36:39], v[170:173], v[194:197], v[36:39]
	v_mfma_f32_16x16x32_bf16 v[32:35], v[178:181], v[194:197], v[32:35]
	v_mfma_f32_16x16x32_bf16 v[20:23], v[170:173], v[202:205], v[20:23]
	v_mfma_f32_16x16x32_bf16 v[16:19], v[178:181], v[202:205], v[16:19]
	v_mfma_f32_16x16x32_bf16 v[4:7], v[170:173], v[210:213], v[4:7]
	v_mfma_f32_16x16x32_bf16 v[0:3], v[178:181], v[210:213], v[0:3]
	s_add_i32 s91, s91, 2
	s_add_u32 s38, s38, 0x100
	s_addc_u32 s39, s39, 0
	s_add_u32 s87, s87, 0x100
	s_addc_u32 s90, s90, 0
	s_cmp_gt_u32 s91, 13
	s_barrier
	s_cbranch_scc0 .LBB0_928
	s_setprio 0
	s_and_b64 vcc, exec, s[12:13]
	s_cbranch_vccz .LBB0_931
	s_barrier

; #define PG8_STAGE(bufoff, gbase, voff) do { _Pragma("unroll") for (int _i = 0; _i < 2; ++_i) \
;         __builtin_amdgcn_global_load_lds((const unsigned*)((const char*)(gbase) + (voff)[_i]), (PG8_LAS unsigned*)(lds + (bufoff) + ldsw + _i * 8192), 16, 0, 0); } while (0)
; #define PG8_LDA(dst, b, h) do { _Pragma("unroll") for (int m = 0; m < 4; ++m) _Pragma("unroll") for (int k = 0; k < 2; ++k) dst[m][k] = *(const PG8_LAS bf16x8*)(lds + PG8_SA(b, h) + aoff + m * 2048 + k * 1024); } while (0)
; #define PG8_LDB(dst, b, h) do { _Pragma("unroll") for (int n = 0; n < 2; ++n) _Pragma("unroll") for (int k = 0; k < 2; ++k) dst[n][k] = *(const PG8_LAS bf16x8*)(lds + PG8_SB(b, h) + boff + n * 2048 + k * 1024); } while (0)
; #define PG8_MMA(ai, bj, At, Bt) do { __builtin_amdgcn_s_setprio(1); _Pragma("unroll") for (int m = 0; m < 4; ++m) _Pragma("unroll") for (int n = 0; n < 2; ++n) _Pragma("unroll") for (int k = 0; k < 2; ++k) \
;         acc[ai][bj][m][n] = __builtin_amdgcn_mfma_f32_16x16x32_bf16(Bt[n][k], At[m][k], acc[ai][bj][m][n], 0, 0, 0); __builtin_amdgcn_s_setprio(0); } while (0)
; #define PG8_WAIT_V(n) asm volatile("s_waitcnt vmcnt(" #n ")" ::: "memory")
; #define PG8_WAIT_L(n) asm volatile("s_waitcnt lgkmcnt(" #n ")" ::: "memory")
; #define PG8_BAR __builtin_amdgcn_s_barrier()
; #define PG8_SCHED __builtin_amdgcn_sched_barrier(0)
; template <class Epi>
; DI void gemm_phase(PG8_LAS unsigned char* lds, const Gemm g, const StaticOrder& S, const Epi& E) {
;     ...
;             PG8_LDB(B0, 0, 0); PG8_LDB(B1, 0, 1); PG8_SCHED; PG8_LDA(At, 0, 0); PG8_STAGE(PG8_SA(1, 1), a1 + hstepA, voffA);
;             PG8_WAIT_V(8); PG8_WAIT_L(0); PG8_BAR; PG8_MMA(0, 0, At, B0); PG8_MMA(0, 1, At, B1); PG8_BAR; PG8_SCHED;
;             PG8_LDA(At, 0, 1); PG8_STAGE(PG8_SB(0, 0), b2, voffB); PG8_STAGE(PG8_SB(0, 1), b2 + hstepB, voffB); PG8_STAGE(PG8_SA(0, 0), a2, voffA);
;             PG8_WAIT_V(8); PG8_WAIT_L(0); PG8_BAR; PG8_MMA(1, 0, At, B0); PG8_MMA(1, 1, At, B1); PG8_BAR; PG8_SCHED;
.LBB0_1061:
	ds_read_b128 v[64:67], v199
	ds_read_b128 v[68:71], v199 offset:1024
	ds_read_b128 v[72:75], v199 offset:2048
	ds_read_b128 v[76:79], v199 offset:3072
	ds_read_b128 v[140:143], v200
	ds_read_b128 v[144:147], v200 offset:1024
	ds_read_b128 v[148:151], v200 offset:2048
	ds_read_b128 v[156:159], v200 offset:3072
	s_add_u32 s38, s36, 0xfffc0080
	s_addc_u32 s39, s37, -1
	s_cmp_eq_u32 s80, 12
	s_cselect_b32 s41, s5, s39
	s_cselect_b32 s40, s7, s38
	s_cselect_b32 s39, s27, s79
	s_cselect_b32 s38, s29, s78
	v_lshl_add_u64 v[194:195], s[36:37], 0, v[170:171]
	s_add_i32 m0, s44, 0xc000
	ds_read_b128 v[178:181], v201
	ds_read_b128 v[182:185], v201 offset:1024
	ds_read_b128 v[186:189], v201 offset:2048
	ds_read_b128 v[190:193], v201 offset:3072
	ds_read_b128 v[202:205], v201 offset:4096
	ds_read_b128 v[206:209], v201 offset:5120
	ds_read_b128 v[210:213], v201 offset:6144
	ds_read_b128 v[214:217], v201 offset:7168
	global_load_lds_dwordx4 v[194:195], off
	v_lshl_add_u64 v[194:195], s[36:37], 0, v[172:173]
	s_add_i32 m0, s44, 0xe000
	s_nop 0
	global_load_lds_dwordx4 v[194:195], off
	s_waitcnt vmcnt(8)
	s_waitcnt lgkmcnt(0)
	s_barrier
	s_waitcnt lgkmcnt(0)
	v_mfma_f32_16x16x32_bf16 v[152:155], v[64:67], v[178:181], v[152:155]
	v_mfma_f32_16x16x32_bf16 v[136:139], v[72:75], v[178:181], v[136:139]
	v_mfma_f32_16x16x32_bf16 v[132:135], v[64:67], v[186:189], v[132:135]
	v_mfma_f32_16x16x32_bf16 v[128:131], v[72:75], v[186:189], v[128:131]
	v_mfma_f32_16x16x32_bf16 v[124:127], v[64:67], v[202:205], v[124:127]
	v_mfma_f32_16x16x32_bf16 v[120:123], v[72:75], v[202:205], v[120:123]
	v_mfma_f32_16x16x32_bf16 v[116:119], v[64:67], v[210:213], v[116:119]
	v_mfma_f32_16x16x32_bf16 v[112:115], v[72:75], v[210:213], v[112:115]
	v_mfma_f32_16x16x32_bf16 v[152:155], v[68:71], v[182:185], v[152:155]
	v_mfma_f32_16x16x32_bf16 v[136:139], v[76:79], v[182:185], v[136:139]
	v_mfma_f32_16x16x32_bf16 v[132:135], v[68:71], v[190:193], v[132:135]
	v_mfma_f32_16x16x32_bf16 v[128:131], v[76:79], v[190:193], v[128:131]
	v_mfma_f32_16x16x32_bf16 v[124:127], v[68:71], v[206:209], v[124:127]
	v_mfma_f32_16x16x32_bf16 v[120:123], v[76:79], v[206:209], v[120:123]
	v_mfma_f32_16x16x32_bf16 v[116:119], v[68:71], v[214:217], v[116:119]
	v_mfma_f32_16x16x32_bf16 v[112:115], v[76:79], v[214:217], v[112:115]
	v_mfma_f32_16x16x32_bf16 v[60:63], v[140:143], v[178:181], v[60:63]
	v_mfma_f32_16x16x32_bf16 v[56:59], v[148:151], v[178:181], v[56:59]
	v_mfma_f32_16x16x32_bf16 v[52:55], v[140:143], v[186:189], v[52:55]
	v_mfma_f32_16x16x32_bf16 v[48:51], v[148:151], v[186:189], v[48:51]
	v_mfma_f32_16x16x32_bf16 v[44:47], v[140:143], v[202:205], v[44:47]
	v_mfma_f32_16x16x32_bf16 v[40:43], v[148:151], v[202:205], v[40:43]
	v_mfma_f32_16x16x32_bf16 v[36:39], v[140:143], v[210:213], v[36:39]
	v_mfma_f32_16x16x32_bf16 v[32:35], v[148:151], v[210:213], v[32:35]
	v_mfma_f32_16x16x32_bf16 v[60:63], v[144:147], v[182:185], v[60:63]
	v_mfma_f32_16x16x32_bf16 v[56:59], v[156:159], v[182:185], v[56:59]
	v_mfma_f32_16x16x32_bf16 v[52:55], v[144:147], v[190:193], v[52:55]
	v_mfma_f32_16x16x32_bf16 v[48:51], v[156:159], v[190:193], v[48:51]
	v_mfma_f32_16x16x32_bf16 v[44:47], v[144:147], v[206:209], v[44:47]
	v_mfma_f32_16x16x32_bf16 v[40:43], v[156:159], v[206:209], v[40:43]
	v_mfma_f32_16x16x32_bf16 v[36:39], v[144:147], v[214:217], v[36:39]
	v_mfma_f32_16x16x32_bf16 v[32:35], v[156:159], v[214:217], v[32:35]
	s_barrier
	s_add_i32 s81, s56, s43
	v_lshl_add_u64 v[194:195], s[38:39], 0, v[162:163]
	s_mov_b32 m0, s81
	ds_read_b128 v[178:181], v201 offset:16384
	ds_read_b128 v[182:185], v201 offset:17408
	ds_read_b128 v[186:189], v201 offset:18432
	ds_read_b128 v[190:193], v201 offset:19456
	ds_read_b128 v[202:205], v201 offset:20480
	ds_read_b128 v[206:209], v201 offset:21504
	ds_read_b128 v[210:213], v201 offset:22528
	ds_read_b128 v[214:217], v201 offset:23552
	global_load_lds_dwordx4 v[194:195], off
	s_add_i32 m0, s81, 0x2000
	s_add_u32 s82, s38, 0x40000
	v_lshl_add_u64 v[222:223], s[38:39], 0, v[166:167]
	s_addc_u32 s83, s39, 0
	s_add_i32 s81, s57, s43
	global_load_lds_dwordx4 v[222:223], off
	v_lshl_add_u64 v[218:219], s[82:83], 0, v[162:163]
	s_mov_b32 m0, s81
	v_lshl_add_u64 v[224:225], s[40:41], 0, v[160:161]
	global_load_lds_dwordx4 v[218:219], off
	v_lshl_add_u64 v[218:219], s[82:83], 0, v[166:167]
	s_add_i32 m0, s81, 0x2000
	v_lshl_add_u64 v[226:227], s[40:41], 0, v[164:165]
	global_load_lds_dwordx4 v[218:219], off
	s_mov_b32 m0, s44
	s_nop 0
	global_load_lds_dwordx4 v[224:225], off
	s_mov_b32 m0, s45
	s_nop 0
	global_load_lds_dwordx4 v[226:227], off
	s_waitcnt vmcnt(8)
	s_waitcnt lgkmcnt(0)
	s_barrier
; #define PG8_STAGE(bufoff, gbase, voff) do { _Pragma("unroll") for (int _i = 0; _i < 2; ++_i) \
;         __builtin_amdgcn_global_load_lds((const unsigned*)((const char*)(gbase) + (voff)[_i]), (PG8_LAS unsigned*)(lds + (bufoff) + ldsw + _i * 8192), 16, 0, 0); } while (0)
; #define PG8_LDA(dst, b, h) do { _Pragma("unroll") for (int m = 0; m < 4; ++m) _Pragma("unroll") for (int k = 0; k < 2; ++k) dst[m][k] = *(const PG8_LAS bf16x8*)(lds + PG8_SA(b, h) + aoff + m * 2048 + k * 1024); } while (0)
; #define PG8_LDB(dst, b, h) do { _Pragma("unroll") for (int n = 0; n < 2; ++n) _Pragma("unroll") for (int k = 0; k < 2; ++k) dst[n][k] = *(const PG8_LAS bf16x8*)(lds + PG8_SB(b, h) + boff + n * 2048 + k * 1024); } while (0)
; #define PG8_MMA(ai, bj, At, Bt) do { __builtin_amdgcn_s_setprio(1); _Pragma("unroll") for (int m = 0; m < 4; ++m) _Pragma("unroll") for (int n = 0; n < 2; ++n) _Pragma("unroll") for (int k = 0; k < 2; ++k) \
;         acc[ai][bj][m][n] = __builtin_amdgcn_mfma_f32_16x16x32_bf16(Bt[n][k], At[m][k], acc[ai][bj][m][n], 0, 0, 0); __builtin_amdgcn_s_setprio(0); } while (0)
; #define PG8_WAIT_V(n) asm volatile("s_waitcnt vmcnt(" #n ")" ::: "memory")
; #define PG8_WAIT_L(n) asm volatile("s_waitcnt lgkmcnt(" #n ")" ::: "memory")
; #define PG8_BAR __builtin_amdgcn_s_barrier()
; #define PG8_SCHED __builtin_amdgcn_sched_barrier(0)
; template <class Epi>
; DI void gemm_phase(PG8_LAS unsigned char* lds, const Gemm g, const StaticOrder& S, const Epi& E) {
;     ...
;             PG8_WAIT_V(8); PG8_WAIT_L(0); PG8_BAR; PG8_MMA(1, 0, At, B0); PG8_MMA(1, 1, At, B1); PG8_BAR; PG8_SCHED;
;             PG8_LDB(B0, 1, 0); PG8_LDB(B1, 1, 1); PG8_SCHED; PG8_LDA(At, 1, 0); PG8_STAGE(PG8_SA(0, 1), a2 + hstepA, voffA);
;             PG8_WAIT_V(8); PG8_WAIT_L(0); PG8_BAR; PG8_MMA(0, 0, At, B0); PG8_MMA(0, 1, At, B1); PG8_BAR; PG8_SCHED;
	s_waitcnt lgkmcnt(0)
	v_mfma_f32_16x16x32_bf16 v[108:111], v[64:67], v[178:181], v[108:111]
	v_mfma_f32_16x16x32_bf16 v[104:107], v[72:75], v[178:181], v[104:107]
	v_mfma_f32_16x16x32_bf16 v[100:103], v[64:67], v[186:189], v[100:103]
	v_mfma_f32_16x16x32_bf16 v[96:99], v[72:75], v[186:189], v[96:99]
	v_mfma_f32_16x16x32_bf16 v[92:95], v[64:67], v[202:205], v[92:95]
	v_mfma_f32_16x16x32_bf16 v[88:91], v[72:75], v[202:205], v[88:91]
	v_mfma_f32_16x16x32_bf16 v[64:67], v[64:67], v[210:213], v[84:87]
	v_mfma_f32_16x16x32_bf16 v[108:111], v[68:71], v[182:185], v[108:111]
	v_mfma_f32_16x16x32_bf16 v[104:107], v[76:79], v[182:185], v[104:107]
	v_mfma_f32_16x16x32_bf16 v[100:103], v[68:71], v[190:193], v[100:103]
	v_mfma_f32_16x16x32_bf16 v[96:99], v[76:79], v[190:193], v[96:99]
	v_mfma_f32_16x16x32_bf16 v[92:95], v[68:71], v[206:209], v[92:95]
	v_mfma_f32_16x16x32_bf16 v[88:91], v[76:79], v[206:209], v[88:91]
	v_mfma_f32_16x16x32_bf16 v[64:67], v[68:71], v[214:217], v[64:67]
	v_mfma_f32_16x16x32_bf16 v[68:71], v[72:75], v[210:213], v[80:83]
	v_mfma_f32_16x16x32_bf16 v[68:71], v[76:79], v[214:217], v[68:71]
	v_mfma_f32_16x16x32_bf16 v[28:31], v[140:143], v[178:181], v[28:31]
	v_mfma_f32_16x16x32_bf16 v[24:27], v[148:151], v[178:181], v[24:27]
	v_mfma_f32_16x16x32_bf16 v[20:23], v[140:143], v[186:189], v[20:23]
	v_mfma_f32_16x16x32_bf16 v[16:19], v[148:151], v[186:189], v[16:19]
	v_mfma_f32_16x16x32_bf16 v[12:15], v[140:143], v[202:205], v[12:15]
	v_mfma_f32_16x16x32_bf16 v[8:11], v[148:151], v[202:205], v[8:11]
	v_mfma_f32_16x16x32_bf16 v[4:7], v[140:143], v[210:213], v[4:7]
	v_mfma_f32_16x16x32_bf16 v[0:3], v[148:151], v[210:213], v[0:3]
	v_mfma_f32_16x16x32_bf16 v[28:31], v[144:147], v[182:185], v[28:31]
	v_mfma_f32_16x16x32_bf16 v[24:27], v[156:159], v[182:185], v[24:27]
	v_mfma_f32_16x16x32_bf16 v[20:23], v[144:147], v[190:193], v[20:23]
	v_mfma_f32_16x16x32_bf16 v[16:19], v[156:159], v[190:193], v[16:19]
	v_mfma_f32_16x16x32_bf16 v[12:15], v[144:147], v[206:209], v[12:15]
	v_mfma_f32_16x16x32_bf16 v[8:11], v[156:159], v[206:209], v[8:11]
	v_mfma_f32_16x16x32_bf16 v[4:7], v[144:147], v[214:217], v[4:7]
	v_mfma_f32_16x16x32_bf16 v[0:3], v[156:159], v[214:217], v[0:3]
	s_barrier
	s_add_i32 s81, 16, 0x18000
	v_add_u32_e32 v84, s81, v198
	s_add_i32 s82, 16, 0x1c000
	ds_read_b128 v[72:75], v84
	ds_read_b128 v[76:79], v84 offset:1024
	ds_read_b128 v[80:83], v84 offset:2048
	ds_read_b128 v[140:143], v84 offset:3072
	v_add_u32_e32 v84, s82, v198
	ds_read_b128 v[144:147], v84
	ds_read_b128 v[148:151], v84 offset:1024
	ds_read_b128 v[156:159], v84 offset:2048
	ds_read_b128 v[178:181], v84 offset:3072
	s_add_u32 s40, s40, 0x40000
	s_addc_u32 s41, s41, 0
	s_mov_b32 m0, s46
	v_lshl_add_u64 v[218:219], s[40:41], 0, v[160:161]
	ds_read_b128 v[84:87], v201 offset:32768
	ds_read_b128 v[182:185], v201 offset:33792
	ds_read_b128 v[186:189], v201 offset:34816
	ds_read_b128 v[190:193], v201 offset:35840
	ds_read_b128 v[202:205], v201 offset:36864
	ds_read_b128 v[206:209], v201 offset:37888
	ds_read_b128 v[210:213], v201 offset:38912
	ds_read_b128 v[214:217], v201 offset:39936
	global_load_lds_dwordx4 v[218:219], off
	v_lshl_add_u64 v[218:219], s[40:41], 0, v[164:165]
	s_mov_b32 m0, s47
	s_nop 0
	global_load_lds_dwordx4 v[218:219], off
	s_waitcnt vmcnt(8)
	s_waitcnt lgkmcnt(0)
	s_barrier
	s_waitcnt lgkmcnt(0)
	v_mfma_f32_16x16x32_bf16 v[152:155], v[72:75], v[84:87], v[152:155]
	v_mfma_f32_16x16x32_bf16 v[136:139], v[80:83], v[84:87], v[136:139]
	v_mfma_f32_16x16x32_bf16 v[132:135], v[72:75], v[186:189], v[132:135]
	v_mfma_f32_16x16x32_bf16 v[128:131], v[80:83], v[186:189], v[128:131]
	v_mfma_f32_16x16x32_bf16 v[124:127], v[72:75], v[202:205], v[124:127]
	v_mfma_f32_16x16x32_bf16 v[120:123], v[80:83], v[202:205], v[120:123]
	v_mfma_f32_16x16x32_bf16 v[116:119], v[72:75], v[210:213], v[116:119]
	v_mfma_f32_16x16x32_bf16 v[112:115], v[80:83], v[210:213], v[112:115]
	v_mfma_f32_16x16x32_bf16 v[152:155], v[76:79], v[182:185], v[152:155]
	v_mfma_f32_16x16x32_bf16 v[136:139], v[140:143], v[182:185], v[136:139]
	v_mfma_f32_16x16x32_bf16 v[132:135], v[76:79], v[190:193], v[132:135]
	v_mfma_f32_16x16x32_bf16 v[128:131], v[140:143], v[190:193], v[128:131]
	v_mfma_f32_16x16x32_bf16 v[124:127], v[76:79], v[206:209], v[124:127]
	v_mfma_f32_16x16x32_bf16 v[120:123], v[140:143], v[206:209], v[120:123]
	v_mfma_f32_16x16x32_bf16 v[116:119], v[76:79], v[214:217], v[116:119]
	v_mfma_f32_16x16x32_bf16 v[112:115], v[140:143], v[214:217], v[112:115]
	v_mfma_f32_16x16x32_bf16 v[60:63], v[144:147], v[84:87], v[60:63]
	v_mfma_f32_16x16x32_bf16 v[56:59], v[156:159], v[84:87], v[56:59]
	v_mfma_f32_16x16x32_bf16 v[52:55], v[144:147], v[186:189], v[52:55]
	v_mfma_f32_16x16x32_bf16 v[48:51], v[156:159], v[186:189], v[48:51]
	v_mfma_f32_16x16x32_bf16 v[44:47], v[144:147], v[202:205], v[44:47]
	v_mfma_f32_16x16x32_bf16 v[40:43], v[156:159], v[202:205], v[40:43]
	v_mfma_f32_16x16x32_bf16 v[36:39], v[144:147], v[210:213], v[36:39]
	v_mfma_f32_16x16x32_bf16 v[32:35], v[156:159], v[210:213], v[32:35]
	v_mfma_f32_16x16x32_bf16 v[60:63], v[148:151], v[182:185], v[60:63]
	v_mfma_f32_16x16x32_bf16 v[56:59], v[178:181], v[182:185], v[56:59]
	v_mfma_f32_16x16x32_bf16 v[52:55], v[148:151], v[190:193], v[52:55]
	v_mfma_f32_16x16x32_bf16 v[48:51], v[178:181], v[190:193], v[48:51]
	v_mfma_f32_16x16x32_bf16 v[44:47], v[148:151], v[206:209], v[44:47]
	v_mfma_f32_16x16x32_bf16 v[40:43], v[178:181], v[206:209], v[40:43]
	v_mfma_f32_16x16x32_bf16 v[36:39], v[148:151], v[214:217], v[36:39]
	v_mfma_f32_16x16x32_bf16 v[32:35], v[178:181], v[214:217], v[32:35]
	s_barrier
; #define PG8_STAGE(bufoff, gbase, voff) do { _Pragma("unroll") for (int _i = 0; _i < 2; ++_i) \
;         __builtin_amdgcn_global_load_lds((const unsigned*)((const char*)(gbase) + (voff)[_i]), (PG8_LAS unsigned*)(lds + (bufoff) + ldsw + _i * 8192), 16, 0, 0); } while (0)
; #define PG8_LDA(dst, b, h) do { _Pragma("unroll") for (int m = 0; m < 4; ++m) _Pragma("unroll") for (int k = 0; k < 2; ++k) dst[m][k] = *(const PG8_LAS bf16x8*)(lds + PG8_SA(b, h) + aoff + m * 2048 + k * 1024); } while (0)
; #define PG8_MMA(ai, bj, At, Bt) do { __builtin_amdgcn_s_setprio(1); _Pragma("unroll") for (int m = 0; m < 4; ++m) _Pragma("unroll") for (int n = 0; n < 2; ++n) _Pragma("unroll") for (int k = 0; k < 2; ++k) \
;         acc[ai][bj][m][n] = __builtin_amdgcn_mfma_f32_16x16x32_bf16(Bt[n][k], At[m][k], acc[ai][bj][m][n], 0, 0, 0); __builtin_amdgcn_s_setprio(0); } while (0)
; #define PG8_WAIT_V(n) asm volatile("s_waitcnt vmcnt(" #n ")" ::: "memory")
; #define PG8_WAIT_L(n) asm volatile("s_waitcnt lgkmcnt(" #n ")" ::: "memory")
; #define PG8_BAR __builtin_amdgcn_s_barrier()
; #define PG8_SCHED __builtin_amdgcn_sched_barrier(0)
; template <class Epi>
; DI void gemm_phase(PG8_LAS unsigned char* lds, const Gemm g, const StaticOrder& S, const Epi& E) {
;     ...
;             PG8_LDA(At, 1, 1); PG8_STAGE(PG8_SB(1, 0), b3, voffB); PG8_STAGE(PG8_SB(1, 1), b3 + hstepB, voffB); PG8_STAGE(PG8_SA(1, 0), a3, voffA);
;             PG8_WAIT_V(8); PG8_WAIT_L(0); PG8_BAR; PG8_MMA(1, 0, At, B0); PG8_MMA(1, 1, At, B1); PG8_BAR; PG8_SCHED;
;         }
;         if (wr == 0) PG8_BAR;
	s_add_i32 s40, s81, s43
	v_lshl_add_u64 v[84:85], v[194:195], 0, s[18:19]
	s_mov_b32 m0, s40
	ds_read_b128 v[182:185], v201 offset:49152
	ds_read_b128 v[186:189], v201 offset:50176
	ds_read_b128 v[190:193], v201 offset:51200
	ds_read_b128 v[202:205], v201 offset:52224
	ds_read_b128 v[206:209], v201 offset:53248
	ds_read_b128 v[210:213], v201 offset:54272
	ds_read_b128 v[214:217], v201 offset:55296
	ds_read_b128 v[218:221], v201 offset:56320
	global_load_lds_dwordx4 v[84:85], off
	s_add_i32 m0, s40, 0x2000
	s_add_u32 s38, s38, 0x40080
	v_lshl_add_u64 v[84:85], v[222:223], 0, s[18:19]
	s_addc_u32 s39, s39, 0
	s_add_i32 s40, s82, s43
	global_load_lds_dwordx4 v[84:85], off
	v_lshl_add_u64 v[84:85], s[38:39], 0, v[162:163]
	s_mov_b32 m0, s40
	s_nop 0
	global_load_lds_dwordx4 v[84:85], off
	v_lshl_add_u64 v[84:85], s[38:39], 0, v[166:167]
	s_add_i32 m0, s40, 0x2000
	s_nop 0
	global_load_lds_dwordx4 v[84:85], off
	v_lshl_add_u64 v[84:85], v[224:225], 0, s[18:19]
	s_mov_b32 m0, s50
	s_nop 0
	global_load_lds_dwordx4 v[84:85], off
	v_lshl_add_u64 v[84:85], v[226:227], 0, s[18:19]
	s_mov_b32 m0, s51
	s_nop 0
	global_load_lds_dwordx4 v[84:85], off
	s_waitcnt vmcnt(8)
	s_waitcnt lgkmcnt(0)
	s_barrier
	s_waitcnt lgkmcnt(0)
	v_mfma_f32_16x16x32_bf16 v[84:87], v[72:75], v[182:185], v[108:111]
	v_mfma_f32_16x16x32_bf16 v[108:111], v[76:79], v[186:189], v[84:87]
	v_mfma_f32_16x16x32_bf16 v[84:87], v[80:83], v[182:185], v[104:107]
	v_mfma_f32_16x16x32_bf16 v[104:107], v[140:143], v[186:189], v[84:87]
	v_mfma_f32_16x16x32_bf16 v[84:87], v[72:75], v[190:193], v[100:103]
	v_mfma_f32_16x16x32_bf16 v[100:103], v[76:79], v[202:205], v[84:87]
	v_mfma_f32_16x16x32_bf16 v[84:87], v[80:83], v[190:193], v[96:99]
	v_mfma_f32_16x16x32_bf16 v[96:99], v[140:143], v[202:205], v[84:87]
	v_mfma_f32_16x16x32_bf16 v[84:87], v[72:75], v[206:209], v[92:95]
	v_mfma_f32_16x16x32_bf16 v[92:95], v[76:79], v[210:213], v[84:87]
	v_mfma_f32_16x16x32_bf16 v[84:87], v[80:83], v[206:209], v[88:91]
	v_mfma_f32_16x16x32_bf16 v[64:67], v[72:75], v[214:217], v[64:67]
	v_mfma_f32_16x16x32_bf16 v[88:91], v[140:143], v[210:213], v[84:87]
	v_mfma_f32_16x16x32_bf16 v[84:87], v[76:79], v[218:221], v[64:67]
	v_mfma_f32_16x16x32_bf16 v[64:67], v[80:83], v[214:217], v[68:71]
	v_mfma_f32_16x16x32_bf16 v[80:83], v[140:143], v[218:221], v[64:67]
	v_mfma_f32_16x16x32_bf16 v[28:31], v[144:147], v[182:185], v[28:31]
	v_mfma_f32_16x16x32_bf16 v[24:27], v[156:159], v[182:185], v[24:27]
	v_mfma_f32_16x16x32_bf16 v[20:23], v[144:147], v[190:193], v[20:23]
	v_mfma_f32_16x16x32_bf16 v[16:19], v[156:159], v[190:193], v[16:19]
	v_mfma_f32_16x16x32_bf16 v[12:15], v[144:147], v[206:209], v[12:15]
	v_mfma_f32_16x16x32_bf16 v[8:11], v[156:159], v[206:209], v[8:11]
	v_mfma_f32_16x16x32_bf16 v[4:7], v[144:147], v[214:217], v[4:7]
	v_mfma_f32_16x16x32_bf16 v[0:3], v[156:159], v[214:217], v[0:3]
	v_mfma_f32_16x16x32_bf16 v[28:31], v[148:151], v[186:189], v[28:31]
	v_mfma_f32_16x16x32_bf16 v[24:27], v[178:181], v[186:189], v[24:27]
	v_mfma_f32_16x16x32_bf16 v[20:23], v[148:151], v[202:205], v[20:23]
	v_mfma_f32_16x16x32_bf16 v[16:19], v[178:181], v[202:205], v[16:19]
	v_mfma_f32_16x16x32_bf16 v[12:15], v[148:151], v[210:213], v[12:15]
	v_mfma_f32_16x16x32_bf16 v[8:11], v[178:181], v[210:213], v[8:11]
	v_mfma_f32_16x16x32_bf16 v[4:7], v[148:151], v[218:221], v[4:7]
	v_mfma_f32_16x16x32_bf16 v[0:3], v[178:181], v[218:221], v[0:3]
	s_add_i32 s80, s80, 2
	s_add_u32 s36, s36, 0x100
	s_addc_u32 s37, s37, 0
	s_add_u32 s78, s78, 0x100
	s_addc_u32 s79, s79, 0
	s_cmp_gt_u32 s80, 13
	s_barrier
	s_cbranch_scc0 .LBB0_1061
	s_setprio 0
	s_and_b64 vcc, exec, s[20:21]
	s_cbranch_vccz .LBB0_1064
	s_barrier

; #define PG8_STAGE(bufoff, gbase, voff) do { _Pragma("unroll") for (int _i = 0; _i < 2; ++_i) \
;         __builtin_amdgcn_global_load_lds((const unsigned*)((const char*)(gbase) + (voff)[_i]), (PG8_LAS unsigned*)(lds + (bufoff) + ldsw + _i * 8192), 16, 0, 0); } while (0)
; #define PG8_LDA(dst, b, h) do { _Pragma("unroll") for (int m = 0; m < 4; ++m) _Pragma("unroll") for (int k = 0; k < 2; ++k) dst[m][k] = *(const PG8_LAS bf16x8*)(lds + PG8_SA(b, h) + aoff + m * 2048 + k * 1024); } while (0)
; #define PG8_LDB(dst, b, h) do { _Pragma("unroll") for (int n = 0; n < 2; ++n) _Pragma("unroll") for (int k = 0; k < 2; ++k) dst[n][k] = *(const PG8_LAS bf16x8*)(lds + PG8_SB(b, h) + boff + n * 2048 + k * 1024); } while (0)
; #define PG8_MMA(ai, bj, At, Bt) do { __builtin_amdgcn_s_setprio(1); _Pragma("unroll") for (int m = 0; m < 4; ++m) _Pragma("unroll") for (int n = 0; n < 2; ++n) _Pragma("unroll") for (int k = 0; k < 2; ++k) \
;         acc[ai][bj][m][n] = __builtin_amdgcn_mfma_f32_16x16x32_bf16(Bt[n][k], At[m][k], acc[ai][bj][m][n], 0, 0, 0); __builtin_amdgcn_s_setprio(0); } while (0)
; #define PG8_WAIT_V(n) asm volatile("s_waitcnt vmcnt(" #n ")" ::: "memory")
; #define PG8_WAIT_L(n) asm volatile("s_waitcnt lgkmcnt(" #n ")" ::: "memory")
; #define PG8_BAR __builtin_amdgcn_s_barrier()
; #define PG8_SCHED __builtin_amdgcn_sched_barrier(0)
; template <class Epi>
; DI void gemm_phase(PG8_LAS unsigned char* lds, const Gemm g, const StaticOrder& S, const Epi& E) {
;     ...
;             PG8_LDB(B0, 0, 0); PG8_LDB(B1, 0, 1); PG8_SCHED; PG8_LDA(At, 0, 0); PG8_STAGE(PG8_SA(1, 1), a1 + hstepA, voffA);
;             PG8_WAIT_V(8); PG8_WAIT_L(0); PG8_BAR; PG8_MMA(0, 0, At, B0); PG8_MMA(0, 1, At, B1); PG8_BAR; PG8_SCHED;
;             PG8_LDA(At, 0, 1); PG8_STAGE(PG8_SB(0, 0), b2, voffB); PG8_STAGE(PG8_SB(0, 1), b2 + hstepB, voffB); PG8_STAGE(PG8_SA(0, 0), a2, voffA);
;             PG8_WAIT_V(8); PG8_WAIT_L(0); PG8_BAR; PG8_MMA(1, 0, At, B0); PG8_MMA(1, 1, At, B1); PG8_BAR; PG8_SCHED;
.LBB0_1224:
	ds_read_b128 v[144:147], v211
	ds_read_b128 v[148:151], v211 offset:1024
	ds_read_b128 v[152:155], v211 offset:2048
	ds_read_b128 v[156:159], v211 offset:3072
	ds_read_b128 v[160:163], v212
	ds_read_b128 v[164:167], v212 offset:1024
	ds_read_b128 v[168:171], v212 offset:2048
	ds_read_b128 v[172:175], v212 offset:3072
	s_add_u32 s22, s20, 0x100
	s_addc_u32 s23, s21, 0
	s_cmp_eq_u32 s57, 40
	s_cselect_b32 s27, s5, s23
	s_cselect_b32 s26, s4, s22
	s_cselect_b32 s25, s19, s56
	s_cselect_b32 s24, s18, s55
	v_lshl_add_u64 v[214:215], s[20:21], 0, v[136:137]
	s_add_i32 m0, s30, 0xc000
	ds_read_b128 v[176:179], v213
	ds_read_b128 v[180:183], v213 offset:1024
	ds_read_b128 v[184:187], v213 offset:2048
	ds_read_b128 v[188:191], v213 offset:3072
	ds_read_b128 v[192:195], v213 offset:4096
	ds_read_b128 v[196:199], v213 offset:5120
	ds_read_b128 v[200:203], v213 offset:6144
	ds_read_b128 v[204:207], v213 offset:7168
	global_load_lds_dwordx4 v[214:215], off
	v_lshl_add_u64 v[214:215], s[20:21], 0, v[138:139]
	s_add_i32 m0, s30, 0xe000
	s_nop 0
	global_load_lds_dwordx4 v[214:215], off
	s_waitcnt vmcnt(8)
	s_waitcnt lgkmcnt(0)
	s_barrier
	s_waitcnt lgkmcnt(0)
	v_mfma_f32_16x16x32_bf16 v[124:127], v[144:147], v[176:179], v[124:127]
	v_mfma_f32_16x16x32_bf16 v[120:123], v[152:155], v[176:179], v[120:123]
	v_mfma_f32_16x16x32_bf16 v[108:111], v[144:147], v[184:187], v[108:111]
	v_mfma_f32_16x16x32_bf16 v[104:107], v[152:155], v[184:187], v[104:107]
	v_mfma_f32_16x16x32_bf16 v[92:95], v[144:147], v[192:195], v[92:95]
	v_mfma_f32_16x16x32_bf16 v[88:91], v[152:155], v[192:195], v[88:91]
	v_mfma_f32_16x16x32_bf16 v[76:79], v[144:147], v[200:203], v[76:79]
	v_mfma_f32_16x16x32_bf16 v[72:75], v[152:155], v[200:203], v[72:75]
	v_mfma_f32_16x16x32_bf16 v[124:127], v[148:151], v[180:183], v[124:127]
	v_mfma_f32_16x16x32_bf16 v[120:123], v[156:159], v[180:183], v[120:123]
	v_mfma_f32_16x16x32_bf16 v[108:111], v[148:151], v[188:191], v[108:111]
	v_mfma_f32_16x16x32_bf16 v[104:107], v[156:159], v[188:191], v[104:107]
	v_mfma_f32_16x16x32_bf16 v[92:95], v[148:151], v[196:199], v[92:95]
	v_mfma_f32_16x16x32_bf16 v[88:91], v[156:159], v[196:199], v[88:91]
	v_mfma_f32_16x16x32_bf16 v[76:79], v[148:151], v[204:207], v[76:79]
	v_mfma_f32_16x16x32_bf16 v[72:75], v[156:159], v[204:207], v[72:75]
	v_mfma_f32_16x16x32_bf16 v[116:119], v[160:163], v[176:179], v[116:119]
	v_mfma_f32_16x16x32_bf16 v[112:115], v[168:171], v[176:179], v[112:115]
	v_mfma_f32_16x16x32_bf16 v[100:103], v[160:163], v[184:187], v[100:103]
	v_mfma_f32_16x16x32_bf16 v[96:99], v[168:171], v[184:187], v[96:99]
	v_mfma_f32_16x16x32_bf16 v[84:87], v[160:163], v[192:195], v[84:87]
	v_mfma_f32_16x16x32_bf16 v[80:83], v[168:171], v[192:195], v[80:83]
	v_mfma_f32_16x16x32_bf16 v[68:71], v[160:163], v[200:203], v[68:71]
	v_mfma_f32_16x16x32_bf16 v[64:67], v[168:171], v[200:203], v[64:67]
	v_mfma_f32_16x16x32_bf16 v[116:119], v[164:167], v[180:183], v[116:119]
	v_mfma_f32_16x16x32_bf16 v[112:115], v[172:175], v[180:183], v[112:115]
	v_mfma_f32_16x16x32_bf16 v[100:103], v[164:167], v[188:191], v[100:103]
	v_mfma_f32_16x16x32_bf16 v[96:99], v[172:175], v[188:191], v[96:99]
	v_mfma_f32_16x16x32_bf16 v[84:87], v[164:167], v[196:199], v[84:87]
	v_mfma_f32_16x16x32_bf16 v[80:83], v[172:175], v[196:199], v[80:83]
	v_mfma_f32_16x16x32_bf16 v[68:71], v[164:167], v[204:207], v[68:71]
	v_mfma_f32_16x16x32_bf16 v[64:67], v[172:175], v[204:207], v[64:67]
	s_barrier
	s_add_i32 s20, s45, s29
	v_lshl_add_u64 v[214:215], s[24:25], 0, v[130:131]
	s_mov_b32 m0, s20
	ds_read_b128 v[176:179], v213 offset:16384
	ds_read_b128 v[180:183], v213 offset:17408
	ds_read_b128 v[184:187], v213 offset:18432
	ds_read_b128 v[188:191], v213 offset:19456
	ds_read_b128 v[192:195], v213 offset:20480
	ds_read_b128 v[196:199], v213 offset:21504
	ds_read_b128 v[200:203], v213 offset:22528
	ds_read_b128 v[204:207], v213 offset:23552
	global_load_lds_dwordx4 v[214:215], off
	s_add_i32 m0, s20, 0x2000
	s_add_u32 s20, s24, 0xb0000
	v_lshl_add_u64 v[216:217], s[24:25], 0, v[134:135]
	s_addc_u32 s21, s25, 0
	s_add_i32 s58, s46, s29
	global_load_lds_dwordx4 v[216:217], off
	v_lshl_add_u64 v[218:219], s[20:21], 0, v[130:131]
	s_mov_b32 m0, s58
	v_lshl_add_u64 v[220:221], s[26:27], 0, v[132:133]
	global_load_lds_dwordx4 v[218:219], off
	v_lshl_add_u64 v[218:219], s[20:21], 0, v[134:135]
	s_add_i32 m0, s58, 0x2000
	s_nop 0
	global_load_lds_dwordx4 v[218:219], off
	v_lshl_add_u64 v[218:219], s[26:27], 0, v[128:129]
	s_mov_b32 m0, s30
	s_nop 0
	global_load_lds_dwordx4 v[218:219], off
	s_mov_b32 m0, s31
	s_nop 0
	global_load_lds_dwordx4 v[220:221], off
	s_waitcnt vmcnt(8)
	s_waitcnt lgkmcnt(0)
	s_barrier
; #define PG8_STAGE(bufoff, gbase, voff) do { _Pragma("unroll") for (int _i = 0; _i < 2; ++_i) \
;         __builtin_amdgcn_global_load_lds((const unsigned*)((const char*)(gbase) + (voff)[_i]), (PG8_LAS unsigned*)(lds + (bufoff) + ldsw + _i * 8192), 16, 0, 0); } while (0)
; #define PG8_LDA(dst, b, h) do { _Pragma("unroll") for (int m = 0; m < 4; ++m) _Pragma("unroll") for (int k = 0; k < 2; ++k) dst[m][k] = *(const PG8_LAS bf16x8*)(lds + PG8_SA(b, h) + aoff + m * 2048 + k * 1024); } while (0)
; #define PG8_LDB(dst, b, h) do { _Pragma("unroll") for (int n = 0; n < 2; ++n) _Pragma("unroll") for (int k = 0; k < 2; ++k) dst[n][k] = *(const PG8_LAS bf16x8*)(lds + PG8_SB(b, h) + boff + n * 2048 + k * 1024); } while (0)
; #define PG8_MMA(ai, bj, At, Bt) do { __builtin_amdgcn_s_setprio(1); _Pragma("unroll") for (int m = 0; m < 4; ++m) _Pragma("unroll") for (int n = 0; n < 2; ++n) _Pragma("unroll") for (int k = 0; k < 2; ++k) \
;         acc[ai][bj][m][n] = __builtin_amdgcn_mfma_f32_16x16x32_bf16(Bt[n][k], At[m][k], acc[ai][bj][m][n], 0, 0, 0); __builtin_amdgcn_s_setprio(0); } while (0)
; #define PG8_WAIT_V(n) asm volatile("s_waitcnt vmcnt(" #n ")" ::: "memory")
; #define PG8_WAIT_L(n) asm volatile("s_waitcnt lgkmcnt(" #n ")" ::: "memory")
; #define PG8_BAR __builtin_amdgcn_s_barrier()
; #define PG8_SCHED __builtin_amdgcn_sched_barrier(0)
; template <class Epi>
; DI void gemm_phase(PG8_LAS unsigned char* lds, const Gemm g, const StaticOrder& S, const Epi& E) {
;     ...
;             PG8_WAIT_V(8); PG8_WAIT_L(0); PG8_BAR; PG8_MMA(1, 0, At, B0); PG8_MMA(1, 1, At, B1); PG8_BAR; PG8_SCHED;
;             PG8_LDB(B0, 1, 0); PG8_LDB(B1, 1, 1); PG8_SCHED; PG8_LDA(At, 1, 0); PG8_STAGE(PG8_SA(0, 1), a2 + hstepA, voffA);
;             PG8_WAIT_V(8); PG8_WAIT_L(0); PG8_BAR; PG8_MMA(0, 0, At, B0); PG8_MMA(0, 1, At, B1); PG8_BAR; PG8_SCHED;
	s_waitcnt lgkmcnt(0)
	v_mfma_f32_16x16x32_bf16 v[60:63], v[144:147], v[176:179], v[60:63]
	v_mfma_f32_16x16x32_bf16 v[56:59], v[152:155], v[176:179], v[56:59]
	v_mfma_f32_16x16x32_bf16 v[44:47], v[144:147], v[184:187], v[44:47]
	v_mfma_f32_16x16x32_bf16 v[40:43], v[152:155], v[184:187], v[40:43]
	v_mfma_f32_16x16x32_bf16 v[32:35], v[144:147], v[192:195], v[32:35]
	v_mfma_f32_16x16x32_bf16 v[24:27], v[152:155], v[192:195], v[24:27]
	v_mfma_f32_16x16x32_bf16 v[12:15], v[144:147], v[200:203], v[12:15]
	v_mfma_f32_16x16x32_bf16 v[8:11], v[152:155], v[200:203], v[8:11]
	v_mfma_f32_16x16x32_bf16 v[60:63], v[148:151], v[180:183], v[60:63]
	v_mfma_f32_16x16x32_bf16 v[56:59], v[156:159], v[180:183], v[56:59]
	v_mfma_f32_16x16x32_bf16 v[44:47], v[148:151], v[188:191], v[44:47]
	v_mfma_f32_16x16x32_bf16 v[40:43], v[156:159], v[188:191], v[40:43]
	v_mfma_f32_16x16x32_bf16 v[32:35], v[148:151], v[196:199], v[32:35]
	v_mfma_f32_16x16x32_bf16 v[24:27], v[156:159], v[196:199], v[24:27]
	v_mfma_f32_16x16x32_bf16 v[12:15], v[148:151], v[204:207], v[12:15]
	v_mfma_f32_16x16x32_bf16 v[8:11], v[156:159], v[204:207], v[8:11]
	v_mfma_f32_16x16x32_bf16 v[52:55], v[160:163], v[176:179], v[52:55]
	v_mfma_f32_16x16x32_bf16 v[48:51], v[168:171], v[176:179], v[48:51]
	v_mfma_f32_16x16x32_bf16 v[36:39], v[160:163], v[184:187], v[36:39]
	v_mfma_f32_16x16x32_bf16 v[28:31], v[168:171], v[184:187], v[28:31]
	v_mfma_f32_16x16x32_bf16 v[20:23], v[160:163], v[192:195], v[20:23]
	v_mfma_f32_16x16x32_bf16 v[16:19], v[168:171], v[192:195], v[16:19]
	v_mfma_f32_16x16x32_bf16 v[4:7], v[160:163], v[200:203], v[4:7]
	v_mfma_f32_16x16x32_bf16 v[0:3], v[168:171], v[200:203], v[0:3]
	v_mfma_f32_16x16x32_bf16 v[52:55], v[164:167], v[180:183], v[52:55]
	v_mfma_f32_16x16x32_bf16 v[48:51], v[172:175], v[180:183], v[48:51]
	v_mfma_f32_16x16x32_bf16 v[36:39], v[164:167], v[188:191], v[36:39]
	v_mfma_f32_16x16x32_bf16 v[28:31], v[172:175], v[188:191], v[28:31]
	v_mfma_f32_16x16x32_bf16 v[20:23], v[164:167], v[196:199], v[20:23]
	v_mfma_f32_16x16x32_bf16 v[16:19], v[172:175], v[196:199], v[16:19]
	v_mfma_f32_16x16x32_bf16 v[4:7], v[164:167], v[204:207], v[4:7]
	v_mfma_f32_16x16x32_bf16 v[0:3], v[172:175], v[204:207], v[0:3]
	s_barrier
	s_add_i32 s58, 16, 0x18000
	s_add_i32 s59, 16, 0x1c000
	v_add_u32_e32 v156, s58, v210
	v_add_u32_e32 v172, s59, v210
	ds_read_b128 v[144:147], v156
	ds_read_b128 v[148:151], v156 offset:1024
	ds_read_b128 v[152:155], v156 offset:2048
	ds_read_b128 v[156:159], v156 offset:3072
	ds_read_b128 v[160:163], v172
	ds_read_b128 v[164:167], v172 offset:1024
	ds_read_b128 v[168:171], v172 offset:2048
	ds_read_b128 v[172:175], v172 offset:3072
	s_add_u32 s20, s26, 0xb0000
	s_addc_u32 s21, s27, 0
	s_mov_b32 m0, s34
	v_lshl_add_u64 v[222:223], s[20:21], 0, v[128:129]
	ds_read_b128 v[176:179], v213 offset:32768
	ds_read_b128 v[180:183], v213 offset:33792
	ds_read_b128 v[184:187], v213 offset:34816
	ds_read_b128 v[188:191], v213 offset:35840
	ds_read_b128 v[192:195], v213 offset:36864
	ds_read_b128 v[196:199], v213 offset:37888
	ds_read_b128 v[200:203], v213 offset:38912
	ds_read_b128 v[204:207], v213 offset:39936
	global_load_lds_dwordx4 v[222:223], off
	v_lshl_add_u64 v[222:223], s[20:21], 0, v[132:133]
	s_mov_b32 m0, s35
	s_nop 0
	global_load_lds_dwordx4 v[222:223], off
	s_waitcnt vmcnt(8)
	s_waitcnt lgkmcnt(0)
	s_barrier
	s_waitcnt lgkmcnt(0)
	v_mfma_f32_16x16x32_bf16 v[124:127], v[144:147], v[176:179], v[124:127]
	v_mfma_f32_16x16x32_bf16 v[120:123], v[152:155], v[176:179], v[120:123]
	v_mfma_f32_16x16x32_bf16 v[108:111], v[144:147], v[184:187], v[108:111]
	v_mfma_f32_16x16x32_bf16 v[104:107], v[152:155], v[184:187], v[104:107]
	v_mfma_f32_16x16x32_bf16 v[92:95], v[144:147], v[192:195], v[92:95]
	v_mfma_f32_16x16x32_bf16 v[88:91], v[152:155], v[192:195], v[88:91]
	v_mfma_f32_16x16x32_bf16 v[76:79], v[144:147], v[200:203], v[76:79]
	v_mfma_f32_16x16x32_bf16 v[72:75], v[152:155], v[200:203], v[72:75]
	v_mfma_f32_16x16x32_bf16 v[124:127], v[148:151], v[180:183], v[124:127]
	v_mfma_f32_16x16x32_bf16 v[120:123], v[156:159], v[180:183], v[120:123]
	v_mfma_f32_16x16x32_bf16 v[108:111], v[148:151], v[188:191], v[108:111]
	v_mfma_f32_16x16x32_bf16 v[104:107], v[156:159], v[188:191], v[104:107]
	v_mfma_f32_16x16x32_bf16 v[92:95], v[148:151], v[196:199], v[92:95]
	v_mfma_f32_16x16x32_bf16 v[88:91], v[156:159], v[196:199], v[88:91]
	v_mfma_f32_16x16x32_bf16 v[76:79], v[148:151], v[204:207], v[76:79]
	v_mfma_f32_16x16x32_bf16 v[72:75], v[156:159], v[204:207], v[72:75]
	v_mfma_f32_16x16x32_bf16 v[116:119], v[160:163], v[176:179], v[116:119]
	v_mfma_f32_16x16x32_bf16 v[112:115], v[168:171], v[176:179], v[112:115]
	v_mfma_f32_16x16x32_bf16 v[100:103], v[160:163], v[184:187], v[100:103]
	v_mfma_f32_16x16x32_bf16 v[96:99], v[168:171], v[184:187], v[96:99]
	v_mfma_f32_16x16x32_bf16 v[84:87], v[160:163], v[192:195], v[84:87]
	v_mfma_f32_16x16x32_bf16 v[80:83], v[168:171], v[192:195], v[80:83]
	v_mfma_f32_16x16x32_bf16 v[68:71], v[160:163], v[200:203], v[68:71]
	v_mfma_f32_16x16x32_bf16 v[64:67], v[168:171], v[200:203], v[64:67]
	v_mfma_f32_16x16x32_bf16 v[116:119], v[164:167], v[180:183], v[116:119]
	v_mfma_f32_16x16x32_bf16 v[112:115], v[172:175], v[180:183], v[112:115]
	v_mfma_f32_16x16x32_bf16 v[100:103], v[164:167], v[188:191], v[100:103]
	v_mfma_f32_16x16x32_bf16 v[96:99], v[172:175], v[188:191], v[96:99]
	v_mfma_f32_16x16x32_bf16 v[84:87], v[164:167], v[196:199], v[84:87]
	v_mfma_f32_16x16x32_bf16 v[80:83], v[172:175], v[196:199], v[80:83]
	v_mfma_f32_16x16x32_bf16 v[68:71], v[164:167], v[204:207], v[68:71]
	v_mfma_f32_16x16x32_bf16 v[64:67], v[172:175], v[204:207], v[64:67]
	s_barrier
; #define PG8_STAGE(bufoff, gbase, voff) do { _Pragma("unroll") for (int _i = 0; _i < 2; ++_i) \
;         __builtin_amdgcn_global_load_lds((const unsigned*)((const char*)(gbase) + (voff)[_i]), (PG8_LAS unsigned*)(lds + (bufoff) + ldsw + _i * 8192), 16, 0, 0); } while (0)
; #define PG8_LDA(dst, b, h) do { _Pragma("unroll") for (int m = 0; m < 4; ++m) _Pragma("unroll") for (int k = 0; k < 2; ++k) dst[m][k] = *(const PG8_LAS bf16x8*)(lds + PG8_SA(b, h) + aoff + m * 2048 + k * 1024); } while (0)
; #define PG8_MMA(ai, bj, At, Bt) do { __builtin_amdgcn_s_setprio(1); _Pragma("unroll") for (int m = 0; m < 4; ++m) _Pragma("unroll") for (int n = 0; n < 2; ++n) _Pragma("unroll") for (int k = 0; k < 2; ++k) \
;         acc[ai][bj][m][n] = __builtin_amdgcn_mfma_f32_16x16x32_bf16(Bt[n][k], At[m][k], acc[ai][bj][m][n], 0, 0, 0); __builtin_amdgcn_s_setprio(0); } while (0)
; #define PG8_WAIT_V(n) asm volatile("s_waitcnt vmcnt(" #n ")" ::: "memory")
; #define PG8_WAIT_L(n) asm volatile("s_waitcnt lgkmcnt(" #n ")" ::: "memory")
; #define PG8_BAR __builtin_amdgcn_s_barrier()
; #define PG8_SCHED __builtin_amdgcn_sched_barrier(0)
; template <class Epi>
; DI void gemm_phase(PG8_LAS unsigned char* lds, const Gemm g, const StaticOrder& S, const Epi& E) {
;     ...
;             PG8_LDA(At, 1, 1); PG8_STAGE(PG8_SB(1, 0), b3, voffB); PG8_STAGE(PG8_SB(1, 1), b3 + hstepB, voffB); PG8_STAGE(PG8_SA(1, 0), a3, voffA);
;             PG8_WAIT_V(8); PG8_WAIT_L(0); PG8_BAR; PG8_MMA(1, 0, At, B0); PG8_MMA(1, 1, At, B1); PG8_BAR; PG8_SCHED;
;         }
;         if (wr == 0) PG8_BAR;
	s_add_i32 s20, s58, s29
	v_lshl_add_u64 v[214:215], v[214:215], 0, s[12:13]
	s_mov_b32 m0, s20
	ds_read_b128 v[176:179], v213 offset:49152
	ds_read_b128 v[180:183], v213 offset:50176
	ds_read_b128 v[184:187], v213 offset:51200
	ds_read_b128 v[188:191], v213 offset:52224
	ds_read_b128 v[192:195], v213 offset:53248
	ds_read_b128 v[196:199], v213 offset:54272
	ds_read_b128 v[200:203], v213 offset:55296
	ds_read_b128 v[204:207], v213 offset:56320
	global_load_lds_dwordx4 v[214:215], off
	s_add_i32 m0, s20, 0x2000
	s_add_u32 s20, s24, 0xb0080
	v_lshl_add_u64 v[214:215], v[216:217], 0, s[12:13]
	s_addc_u32 s21, s25, 0
	s_add_i32 s24, s59, s29
	global_load_lds_dwordx4 v[214:215], off
	v_lshl_add_u64 v[214:215], s[20:21], 0, v[130:131]
	s_mov_b32 m0, s24
	s_nop 0
	global_load_lds_dwordx4 v[214:215], off
	v_lshl_add_u64 v[214:215], s[20:21], 0, v[134:135]
	s_add_i32 m0, s24, 0x2000
	s_nop 0
	global_load_lds_dwordx4 v[214:215], off
	v_lshl_add_u64 v[214:215], v[218:219], 0, s[12:13]
	s_mov_b32 m0, s39
	s_nop 0
	global_load_lds_dwordx4 v[214:215], off
	v_lshl_add_u64 v[214:215], v[220:221], 0, s[12:13]
	s_mov_b32 m0, s40
	s_nop 0
	global_load_lds_dwordx4 v[214:215], off
	s_waitcnt vmcnt(8)
	s_waitcnt lgkmcnt(0)
	s_barrier
	s_waitcnt lgkmcnt(0)
	v_mfma_f32_16x16x32_bf16 v[60:63], v[144:147], v[176:179], v[60:63]
	v_mfma_f32_16x16x32_bf16 v[56:59], v[152:155], v[176:179], v[56:59]
	v_mfma_f32_16x16x32_bf16 v[44:47], v[144:147], v[184:187], v[44:47]
	v_mfma_f32_16x16x32_bf16 v[40:43], v[152:155], v[184:187], v[40:43]
	v_mfma_f32_16x16x32_bf16 v[32:35], v[144:147], v[192:195], v[32:35]
	v_mfma_f32_16x16x32_bf16 v[24:27], v[152:155], v[192:195], v[24:27]
	v_mfma_f32_16x16x32_bf16 v[12:15], v[144:147], v[200:203], v[12:15]
	v_mfma_f32_16x16x32_bf16 v[8:11], v[152:155], v[200:203], v[8:11]
	v_mfma_f32_16x16x32_bf16 v[60:63], v[148:151], v[180:183], v[60:63]
	v_mfma_f32_16x16x32_bf16 v[56:59], v[156:159], v[180:183], v[56:59]
	v_mfma_f32_16x16x32_bf16 v[44:47], v[148:151], v[188:191], v[44:47]
	v_mfma_f32_16x16x32_bf16 v[40:43], v[156:159], v[188:191], v[40:43]
	v_mfma_f32_16x16x32_bf16 v[32:35], v[148:151], v[196:199], v[32:35]
	v_mfma_f32_16x16x32_bf16 v[24:27], v[156:159], v[196:199], v[24:27]
	v_mfma_f32_16x16x32_bf16 v[12:15], v[148:151], v[204:207], v[12:15]
	v_mfma_f32_16x16x32_bf16 v[8:11], v[156:159], v[204:207], v[8:11]
	v_mfma_f32_16x16x32_bf16 v[52:55], v[160:163], v[176:179], v[52:55]
	v_mfma_f32_16x16x32_bf16 v[48:51], v[168:171], v[176:179], v[48:51]
	v_mfma_f32_16x16x32_bf16 v[36:39], v[160:163], v[184:187], v[36:39]
	v_mfma_f32_16x16x32_bf16 v[28:31], v[168:171], v[184:187], v[28:31]
	v_mfma_f32_16x16x32_bf16 v[20:23], v[160:163], v[192:195], v[20:23]
	v_mfma_f32_16x16x32_bf16 v[16:19], v[168:171], v[192:195], v[16:19]
	v_mfma_f32_16x16x32_bf16 v[4:7], v[160:163], v[200:203], v[4:7]
	v_mfma_f32_16x16x32_bf16 v[0:3], v[168:171], v[200:203], v[0:3]
	v_mfma_f32_16x16x32_bf16 v[52:55], v[164:167], v[180:183], v[52:55]
	v_mfma_f32_16x16x32_bf16 v[48:51], v[172:175], v[180:183], v[48:51]
	v_mfma_f32_16x16x32_bf16 v[36:39], v[164:167], v[188:191], v[36:39]
	v_mfma_f32_16x16x32_bf16 v[28:31], v[172:175], v[188:191], v[28:31]
	v_mfma_f32_16x16x32_bf16 v[20:23], v[164:167], v[196:199], v[20:23]
	v_mfma_f32_16x16x32_bf16 v[16:19], v[172:175], v[196:199], v[16:19]
	v_mfma_f32_16x16x32_bf16 v[4:7], v[164:167], v[204:207], v[4:7]
	v_mfma_f32_16x16x32_bf16 v[0:3], v[172:175], v[204:207], v[0:3]
	s_add_i32 s57, s57, 2
	s_add_u32 s55, s55, 0x100
	s_addc_u32 s56, s56, 0
	s_cmp_gt_u32 s57, 41
	s_mov_b64 s[20:21], s[22:23]
	s_barrier
	s_cbranch_scc0 .LBB0_1224
	s_setprio 0
	s_and_b64 vcc, exec, s[14:15]
	s_cbranch_vccz .LBB0_1227
	s_barrier
